# RG-LRU gate GEMM epilogue arithmetic rewritten by hand: 8 elements in flight, packed f32 adds/muls/fmas, select instead of divergent branches (same formulas and operation order)
# speedup vs baseline: 1.0112x; 1.0069x over previous
; #define PG8_WAIT_V(n) asm volatile("s_waitcnt vmcnt(" #n ")" ::: "memory")
; #define PG8_BAR __builtin_amdgcn_s_barrier()
;     __device__ __forceinline__ bool next(int i, Unit& u) const {
;         const long L = (long)i * G + c; const int nwg = nM * nN; if (L >= nwg) return false;
;         int wgid = (int)L; { const int q = nwg / 8, r = nwg % 8, xcd = wgid % 8, off = wgid / 8; wgid = (xcd < r ? xcd * (q + 1) : r * (q + 1) + (xcd - r) * q) + off; }
;         const int nig = 8 * nN, gid = wgid / nig, fm = gid * 8, gsz = (nM - fm) < 8 ? (nM - fm) : 8;
;         u.pm = fm + ((wgid % nig) % gsz); u.pn = (wgid % nig) / gsz; u.tag = 0;
;         u.A = A + (size_t)u.pm * a_tile + (size_t)((u.pn >> a_sh) * a_mul); u.B = B + (size_t)u.pn * b_tile; u.nt = nt; return true;
; template <class Epi, class S_t>
; __device__ __forceinline__ void gemm_phase(LAS unsigned char* lds, int lda, int ldb, const S_t& S, const Epi& E) {
;     ...
;     for (int i = 0; i < 2; ++i) { int R, C; stage_rc(tid * 16 + i * 8192, R, C); const int Rb = Epi::PERM ? ((R & ~31) + perm32(R & 31)) : R;
;         voffA[i] = (unsigned)(R * lda + C) * 2u; voffB[i] = (unsigned)(Rb * ldb + C) * 2u; }
;     const size_t kstep = (size_t)(BK * 2);
;     const size_t hstepA = (size_t)HALF * lda * 2, hstepB = (size_t)HALF * ldb * 2;
;     const unsigned ldsw = (unsigned)wid * 1024u;
;     const int aoff = lds_byte(wr * 64 + fr, fq * 8), boff = lds_byte(wc * 32 + fr, fq * 8);
;     ...
;     Unit cur, nxt; int ui = 0;
;     if (!S.next(0, cur)) return;
;     f32x4 acc[2][2][4][2];
; #pragma unroll
;     for (int a = 0; a < 2; ++a)
; #pragma unroll
;         for (int b = 0; b < 2; ++b)
; #pragma unroll
;             for (int m = 0; m < 4; ++m)
; #pragma unroll
;                 for (int n = 0; n < 2; ++n) acc[a][b][m][n] = (f32x4){0.f, 0.f, 0.f, 0.f};
;     bf16x8 At[4][2], B0[2][2], B1[2][2];
;     const char* cA = cur.A; const char* cB = cur.B;
;     PG8_STAGE(PG8_SB(0, 0), cB, voffB); PG8_STAGE(PG8_SA(0, 0), cA, voffA); PG8_STAGE(PG8_SB(0, 1), cB + hstepB, voffB); PG8_STAGE(PG8_SA(0, 1), cA + hstepA, voffA);
;     if (wr == 1) PG8_BAR;
;     PG8_WAIT_V(4); PG8_BAR;
;     PG8_STAGE(PG8_SB(1, 0), cB + kstep, voffB); PG8_STAGE(PG8_SA(1, 0), cA + kstep, voffA); PG8_STAGE(PG8_SB(1, 1), cB + hstepB + kstep, voffB);
;     PG8_WAIT_V(6); PG8_BAR;
.LBB0_542:
	s_and_b32 s21, s1, 0xff
	s_add_u32 s44, s84, 0x6d00000
	s_addc_u32 s45, s85, 0
	s_add_u32 s10, s84, 0xc00000
	s_addc_u32 s11, s85, 0
	s_lshl_b32 s4, s4, 5
	s_mov_b64 s[12:13], 0x80
	s_and_b32 s4, s4, 0x60
	s_add_i32 m0, s53, 0x18000
	v_lshl_add_u64 v[6:7], v[6:7], 0, s[12:13]
	s_lshl_b32 s1, s0, 13
	s_lshl_b32 s14, s4, 7
	s_waitcnt vmcnt(4)
	s_barrier
	global_load_lds_dwordx4 v[6:7], off
	v_lshl_add_u64 v[4:5], v[4:5], 0, s[12:13]
	s_add_i32 m0, s53, 0x1a000
	s_add_i32 s16, s53, 0x8000
	s_add_i32 s17, s53, 0xa000
	global_load_lds_dwordx4 v[4:5], off
	v_lshl_add_u64 v[2:3], v[2:3], 0, s[12:13]
	s_mov_b32 m0, s16
	s_add_u32 s6, s62, 0x10080
	global_load_lds_dwordx4 v[2:3], off
	v_lshl_add_u64 v[0:1], v[0:1], 0, s[12:13]
	s_mov_b32 m0, s17
	s_addc_u32 s7, s63, 0
	global_load_lds_dwordx4 v[0:1], off
	s_add_i32 m0, s53, 0x1c000
	v_lshl_add_u64 v[0:1], s[6:7], 0, v[188:189]
	global_load_lds_dwordx4 v[0:1], off
	v_lshl_add_u64 v[0:1], s[6:7], 0, v[192:193]
	s_add_i32 m0, s53, 0x1e000
	s_add_i32 s88, 0, 0x10000
	global_load_lds_dwordx4 v[0:1], off
	v_lshrrev_b32_e32 v1, 1, v8
	v_and_b32_e32 v1, 24, v1
	v_and_b32_e32 v0, 15, v8
	v_lshlrev_b32_e32 v2, 1, v1
	v_lshl_or_b32 v215, s0, 6, v0
	v_lshl_or_b32 v0, v0, 6, v2
	v_lshlrev_b32_e32 v2, 2, v8
	v_and_b32_e32 v2, 32, v2
	s_waitcnt vmcnt(6)
	v_bitop3_b32 v3, v0, s1, v2 bitop3:0xde
	v_bitop3_b32 v219, v0, s14, v2 bitop3:0xde
	s_add_i32 s89, 0, 0x14000
	s_ashr_i32 s93, s86, 31
	s_mov_b32 s94, s86
	v_or_b32_e32 v221, s4, v1
	v_mov_b64_e32 v[194:195], 0x23f
	v_add_u32_e32 v226, s88, v219
	v_add_u32_e32 v227, 0, v3
	v_add_u32_e32 v228, s89, v219
	s_mov_b32 s4, 0xbd000000
	v_mov_b32_e32 v229, 0x3e2aaaab
	s_mov_b64 s[58:59], s[62:63]
	s_mov_b64 s[56:57], s[60:61]
	s_barrier
	s_branch .LBB0_544
.LBB0_544:
	s_add_i32 s20, s20, 1
	s_mul_i32 s0, s20, s93
	s_mul_hi_u32 s1, s20, s94
	s_add_i32 s1, s1, s0
	s_mul_i32 s0, s20, s94
	s_add_u32 s0, s0, s21
	s_addc_u32 s1, s1, 0
	v_cmp_gt_i64_e64 s[6:7], s[0:1], v[194:195]
	s_and_b64 vcc, exec, s[6:7]
	s_cbranch_vccnz .LBB0_546
	s_ashr_i32 s1, s0, 31
	s_lshr_b32 s1, s1, 29
	s_add_i32 s1, s0, s1
	s_ashr_i32 s14, s1, 3
	s_and_b32 s1, s1, -8
	s_sub_i32 s0, s0, s1
	s_cmp_lt_i32 s0, 0
	s_movk_i32 s1, 0x49
	s_cselect_b32 s1, s1, 0x48
	s_mul_i32 s0, s0, s1
	s_add_i32 s0, s0, s14
	s_ashr_i32 s1, s0, 31
	s_lshr_b32 s1, s1, 25
	s_add_i32 s1, s0, s1
	s_ashr_i32 s14, s1, 7
	s_lshl_b32 s15, s14, 3
	s_sub_i32 s14, 36, s15
	s_min_i32 s18, s14, 8
	s_abs_i32 s14, s18
	v_cvt_f32_u32_e32 v0, s14
	s_sub_i32 s33, 0, s14
	s_and_b32 s1, s1, 0xffffff80
	s_sub_i32 s0, s0, s1
	v_rcp_iflag_f32_e32 v0, v0
	s_abs_i32 s1, s0
	s_xor_b32 s19, s0, s18
	s_ashr_i32 s19, s19, 31
	v_mul_f32_e32 v0, 0x4f7ffffe, v0
	v_cvt_u32_f32_e32 v0, v0
	s_nop 0
	v_readfirstlane_b32 s43, v0
	s_mul_i32 s33, s33, s43
	s_mul_hi_u32 s33, s43, s33
	s_add_i32 s43, s43, s33
	s_mul_hi_u32 s33, s1, s43
	s_mul_i32 s43, s33, s14
	s_sub_i32 s1, s1, s43
	s_add_i32 s56, s33, 1
	s_sub_i32 s43, s1, s14
	s_cmp_ge_u32 s1, s14
	s_cselect_b32 s33, s56, s33
	s_cselect_b32 s1, s43, s1
	s_add_i32 s43, s33, 1
	s_cmp_ge_u32 s1, s14
	s_cselect_b32 s1, s43, s33
	s_xor_b32 s1, s1, s19
	s_sub_i32 s14, s1, s19
	s_mul_i32 s1, s14, s18
	s_sub_i32 s0, s0, s1
	s_add_i32 s18, s15, s0
	s_ashr_i32 s19, s18, 31
	s_lshl_b64 s[0:1], s[18:19], 20
	s_add_u32 s0, s8, s0
	s_addc_u32 s1, s9, s1
	s_lshl_b32 s15, s14, 8
	s_and_b32 s15, s15, 0xfffffe00
	s_ashr_i32 s19, s15, 31
	s_add_u32 s56, s0, s15
	s_addc_u32 s57, s1, s19
	s_ashr_i32 s15, s14, 31
	s_lshl_b64 s[0:1], s[14:15], 17
	s_add_u32 s58, s35, s0
	s_addc_u32 s59, s52, s1

; #define PG8_STAGE(bufoff, gbase, voff) do { _Pragma("unroll") for (int _i = 0; _i < 2; ++_i) \
;         __builtin_amdgcn_global_load_lds((const unsigned*)((const char*)(gbase) + (voff)[_i]), (LAS unsigned*)(lds + (bufoff) + ldsw + _i * 8192), 16, 0, 0); } while (0)
; #define PG8_LDA(dst, b, h) do { _Pragma("unroll") for (int m = 0; m < 4; ++m) _Pragma("unroll") for (int k = 0; k < 2; ++k) dst[m][k] = *(const LAS bf16x8*)(lds + PG8_SA(b, h) + aoff + m * 2048 + k * 1024); } while (0)
; #define PG8_LDB(dst, b, h) do { _Pragma("unroll") for (int n = 0; n < 2; ++n) _Pragma("unroll") for (int k = 0; k < 2; ++k) dst[n][k] = *(const LAS bf16x8*)(lds + PG8_SB(b, h) + boff + n * 2048 + k * 1024); } while (0)
; #define PG8_MMA(ai, bj, At, Bt) do { __builtin_amdgcn_s_setprio(1); _Pragma("unroll") for (int m = 0; m < 4; ++m) _Pragma("unroll") for (int n = 0; n < 2; ++n) _Pragma("unroll") for (int k = 0; k < 2; ++k) \
;         acc[ai][bj][m][n] = __builtin_amdgcn_mfma_f32_16x16x32_bf16(Bt[n][k], At[m][k], acc[ai][bj][m][n], 0, 0, 0); __builtin_amdgcn_s_setprio(0); } while (0)
; #define PG8_BAR __builtin_amdgcn_s_barrier()
; template <class Epi, class S_t>
; __device__ __forceinline__ void gemm_phase(LAS unsigned char* lds, int lda, int ldb, const S_t& S, const Epi& E) {
;     ...
;             const char* a1 = cA + (size_t)(t + 1) * kstep;
;             const char* a2 = last ? nA : cA + (size_t)(t + 2) * kstep; const char* b2 = last ? nB : cB + (size_t)(t + 2) * kstep;
;             const char* a3 = a2 + kstep; const char* b3 = b2 + kstep;
;             PG8_LDB(B0, 0, 0); PG8_SCHED; PG8_LDA(At, 0, 0); PG8_STAGE(PG8_SA(1, 1), a1 + hstepA, voffA);
;             PG8_WAIT_L(8); PG8_BAR; PG8_WAIT_L(0); PG8_MMA(0, 0, At, B0); PG8_BAR; PG8_SCHED;
;             PG8_LDB(B1, 0, 1); PG8_STAGE(PG8_SB(0, 0), b2, voffB);
;             PG8_BAR; PG8_WAIT_L(0); PG8_MMA(0, 1, At, B1); PG8_BAR;
;             PG8_LDA(At, 0, 1); PG8_STAGE(PG8_SA(0, 0), a2, voffA);
;             PG8_BAR; PG8_WAIT_L(0); PG8_MMA(1, 0, At, B0); PG8_BAR; PG8_SCHED;
;             PG8_STAGE(PG8_SB(0, 1), b2 + hstepB, voffB);
;             PG8_WAIT_V(6); PG8_BAR; PG8_MMA(1, 1, At, B1); PG8_BAR;
;             PG8_LDB(B0, 1, 0); PG8_SCHED; PG8_LDA(At, 1, 0); PG8_STAGE(PG8_SA(0, 1), a2 + hstepA, voffA);
;             PG8_WAIT_L(8); PG8_BAR; PG8_WAIT_L(0); PG8_MMA(0, 0, At, B0); PG8_BAR; PG8_SCHED;
.LBB0_547:
	s_add_u32 s15, s60, s0
	s_addc_u32 s19, s61, 0
	s_add_u32 s1, s15, 0x100
	s_addc_u32 s33, s19, 0
	s_and_b64 s[70:71], s[68:69], exec
	s_cselect_b32 s75, s57, s33
	s_cselect_b32 s74, s56, s1
	s_add_u32 s0, s62, s0
	s_addc_u32 s1, s63, 0
	s_add_u32 s33, s0, 0x100
	s_addc_u32 s43, s1, 0
	s_and_b64 s[0:1], s[68:69], exec
	s_cselect_b32 s79, s59, s43
	s_cselect_b32 s78, s58, s33
	s_add_u32 s82, s15, 0x80080
	s_addc_u32 s83, s19, 0
	s_add_i32 vcc_hi, s88, s64
	s_add_i32 m0, s53, 0xc000
	s_add_i32 s65, s53, 0xe000
	s_add_i32 s33, vcc_hi, 0x2000
	s_add_u32 s72, s78, 0x10000
	s_addc_u32 s73, s79, 0
	s_add_i32 vcc_lo, s89, s64
	s_add_i32 s43, vcc_lo, 0x2000
	s_add_i32 s90, 0, 0x18000
	ds_read_b128 v[32:35], v226
	ds_read_b128 v[36:39], v226 offset:1024
	ds_read_b128 v[48:51], v226 offset:2048
	ds_read_b128 v[52:55], v226 offset:3072
	s_add_u32 s70, s74, 0x80000
	s_addc_u32 s71, s75, 0
	s_add_i32 s19, s90, s64
	s_add_i32 s91, 0, 0x1c000
	s_add_i32 s15, s19, 0x2000
	s_add_u32 s68, s78, 0x10080
	s_addc_u32 s69, s79, 0
	s_add_i32 s1, s91, s64
	s_add_i32 s0, s1, 0x2000
	ds_read_b128 v[56:59], v227
	ds_read_b128 v[64:67], v227 offset:1024
	ds_read_b128 v[68:71], v227 offset:2048
	ds_read_b128 v[76:79], v227 offset:3072
	ds_read_b128 v[96:99], v227 offset:4096
	ds_read_b128 v[116:119], v227 offset:5120
	ds_read_b128 v[136:139], v227 offset:6144
	ds_read_b128 v[156:159], v227 offset:7168
	global_load_lds_dwordx4 v186, s[82:83]
	s_mov_b32 m0, s65
	s_nop 0
	global_load_lds_dwordx4 v190, s[82:83]
	s_waitcnt lgkmcnt(8)
	s_barrier
	s_waitcnt lgkmcnt(0)
	s_setprio 1
	s_waitcnt lgkmcnt(0)
	v_mfma_f32_16x16x32_bf16 v[172:175], v[32:35], v[56:59], v[172:175]
	v_mfma_f32_16x16x32_bf16 v[168:171], v[48:51], v[56:59], v[168:171]
	v_mfma_f32_16x16x32_bf16 v[152:155], v[32:35], v[68:71], v[152:155]
	v_mfma_f32_16x16x32_bf16 v[148:151], v[48:51], v[68:71], v[148:151]
	v_mfma_f32_16x16x32_bf16 v[132:135], v[32:35], v[96:99], v[132:135]
	v_mfma_f32_16x16x32_bf16 v[128:131], v[48:51], v[96:99], v[128:131]
	v_mfma_f32_16x16x32_bf16 v[112:115], v[32:35], v[136:139], v[112:115]
	v_mfma_f32_16x16x32_bf16 v[108:111], v[48:51], v[136:139], v[108:111]
	v_mfma_f32_16x16x32_bf16 v[172:175], v[36:39], v[64:67], v[172:175]
	v_mfma_f32_16x16x32_bf16 v[168:171], v[52:55], v[64:67], v[168:171]
	v_mfma_f32_16x16x32_bf16 v[152:155], v[36:39], v[76:79], v[152:155]
	v_mfma_f32_16x16x32_bf16 v[148:151], v[52:55], v[76:79], v[148:151]
	v_mfma_f32_16x16x32_bf16 v[132:135], v[36:39], v[116:119], v[132:135]
	v_mfma_f32_16x16x32_bf16 v[128:131], v[52:55], v[116:119], v[128:131]
	v_mfma_f32_16x16x32_bf16 v[112:115], v[36:39], v[156:159], v[112:115]
	v_mfma_f32_16x16x32_bf16 v[108:111], v[52:55], v[156:159], v[108:111]
	s_setprio 0
	s_barrier
	s_mov_b32 m0, vcc_hi
	s_add_u32 s100, s78, s12
	s_addc_u32 s101, s79, s13
	ds_read_b128 v[176:179], v228
	ds_read_b128 v[180:183], v228 offset:1024
	ds_read_b128 v[196:199], v228 offset:2048
	ds_read_b128 v[200:203], v228 offset:3072
	global_load_lds_dwordx4 v188, s[78:79]
	s_mov_b32 m0, s33
	s_nop 0
	global_load_lds_dwordx4 v192, s[78:79]
	s_barrier
	s_waitcnt lgkmcnt(0)
	s_setprio 1
	s_waitcnt lgkmcnt(0)
	v_mfma_f32_16x16x32_bf16 v[160:163], v[176:179], v[56:59], v[160:163]
	v_mfma_f32_16x16x32_bf16 v[56:59], v[196:199], v[56:59], v[164:167]
	v_mfma_f32_16x16x32_bf16 v[160:163], v[180:183], v[64:67], v[160:163]
	v_mfma_f32_16x16x32_bf16 v[56:59], v[200:203], v[64:67], v[56:59]
	v_mfma_f32_16x16x32_bf16 v[64:67], v[176:179], v[68:71], v[140:143]
	v_mfma_f32_16x16x32_bf16 v[68:71], v[196:199], v[68:71], v[144:147]
	v_mfma_f32_16x16x32_bf16 v[100:103], v[176:179], v[136:139], v[100:103]
	v_mfma_f32_16x16x32_bf16 v[104:107], v[196:199], v[136:139], v[104:107]
	v_mfma_f32_16x16x32_bf16 v[64:67], v[180:183], v[76:79], v[64:67]
	v_mfma_f32_16x16x32_bf16 v[68:71], v[200:203], v[76:79], v[68:71]
	v_mfma_f32_16x16x32_bf16 v[76:79], v[176:179], v[96:99], v[120:123]
	v_mfma_f32_16x16x32_bf16 v[96:99], v[196:199], v[96:99], v[124:127]
	v_mfma_f32_16x16x32_bf16 v[100:103], v[180:183], v[156:159], v[100:103]
	v_mfma_f32_16x16x32_bf16 v[104:107], v[200:203], v[156:159], v[104:107]
	v_mfma_f32_16x16x32_bf16 v[76:79], v[180:183], v[116:119], v[76:79]
	v_mfma_f32_16x16x32_bf16 v[96:99], v[200:203], v[116:119], v[96:99]
	s_setprio 0
	s_mov_b32 m0, s53
	s_add_u32 s98, s74, s12
	s_addc_u32 s99, s75, s13
	s_barrier
	ds_read_b128 v[116:119], v227 offset:16384
	ds_read_b128 v[120:123], v227 offset:17408
	ds_read_b128 v[124:127], v227 offset:18432
	ds_read_b128 v[136:139], v227 offset:19456
	ds_read_b128 v[140:143], v227 offset:20480
	ds_read_b128 v[144:147], v227 offset:21504
	ds_read_b128 v[156:159], v227 offset:22528
	ds_read_b128 v[164:167], v227 offset:23552
	global_load_lds_dwordx4 v186, s[74:75]
	s_mov_b32 m0, s95
	s_nop 0
	global_load_lds_dwordx4 v190, s[74:75]
	s_barrier
	s_waitcnt lgkmcnt(0)
	s_setprio 1
	s_waitcnt lgkmcnt(0)
	v_mfma_f32_16x16x32_bf16 v[92:95], v[32:35], v[116:119], v[92:95]
	v_mfma_f32_16x16x32_bf16 v[88:91], v[48:51], v[116:119], v[88:91]
	v_mfma_f32_16x16x32_bf16 v[72:75], v[32:35], v[124:127], v[72:75]
	v_mfma_f32_16x16x32_bf16 v[60:63], v[48:51], v[124:127], v[60:63]
	v_mfma_f32_16x16x32_bf16 v[28:31], v[32:35], v[140:143], v[28:31]
	v_mfma_f32_16x16x32_bf16 v[24:27], v[48:51], v[140:143], v[24:27]
	v_mfma_f32_16x16x32_bf16 v[12:15], v[32:35], v[156:159], v[12:15]
	v_mfma_f32_16x16x32_bf16 v[8:11], v[48:51], v[156:159], v[8:11]
	v_mfma_f32_16x16x32_bf16 v[92:95], v[36:39], v[120:123], v[92:95]
	v_mfma_f32_16x16x32_bf16 v[88:91], v[52:55], v[120:123], v[88:91]
	v_mfma_f32_16x16x32_bf16 v[72:75], v[36:39], v[136:139], v[72:75]
	v_mfma_f32_16x16x32_bf16 v[60:63], v[52:55], v[136:139], v[60:63]
	v_mfma_f32_16x16x32_bf16 v[28:31], v[36:39], v[144:147], v[28:31]
	v_mfma_f32_16x16x32_bf16 v[24:27], v[52:55], v[144:147], v[24:27]
	v_mfma_f32_16x16x32_bf16 v[12:15], v[36:39], v[164:167], v[12:15]
	v_mfma_f32_16x16x32_bf16 v[8:11], v[52:55], v[164:167], v[8:11]
	s_setprio 0
	s_barrier
; #define PG8_STAGE(bufoff, gbase, voff) do { _Pragma("unroll") for (int _i = 0; _i < 2; ++_i) \
;         __builtin_amdgcn_global_load_lds((const unsigned*)((const char*)(gbase) + (voff)[_i]), (LAS unsigned*)(lds + (bufoff) + ldsw + _i * 8192), 16, 0, 0); } while (0)
; #define PG8_LDA(dst, b, h) do { _Pragma("unroll") for (int m = 0; m < 4; ++m) _Pragma("unroll") for (int k = 0; k < 2; ++k) dst[m][k] = *(const LAS bf16x8*)(lds + PG8_SA(b, h) + aoff + m * 2048 + k * 1024); } while (0)
; #define PG8_LDB(dst, b, h) do { _Pragma("unroll") for (int n = 0; n < 2; ++n) _Pragma("unroll") for (int k = 0; k < 2; ++k) dst[n][k] = *(const LAS bf16x8*)(lds + PG8_SB(b, h) + boff + n * 2048 + k * 1024); } while (0)
; #define PG8_MMA(ai, bj, At, Bt) do { __builtin_amdgcn_s_setprio(1); _Pragma("unroll") for (int m = 0; m < 4; ++m) _Pragma("unroll") for (int n = 0; n < 2; ++n) _Pragma("unroll") for (int k = 0; k < 2; ++k) \
;         acc[ai][bj][m][n] = __builtin_amdgcn_mfma_f32_16x16x32_bf16(Bt[n][k], At[m][k], acc[ai][bj][m][n], 0, 0, 0); __builtin_amdgcn_s_setprio(0); } while (0)
; #define PG8_WAIT_V(n) asm volatile("s_waitcnt vmcnt(" #n ")" ::: "memory")
; #define PG8_WAIT_L(n) asm volatile("s_waitcnt lgkmcnt(" #n ")" ::: "memory")
; #define PG8_BAR __builtin_amdgcn_s_barrier()
; #define PG8_SCHED __builtin_amdgcn_sched_barrier(0)
; template <class Epi, class S_t>
; __device__ __forceinline__ void gemm_phase(LAS unsigned char* lds, int lda, int ldb, const S_t& S, const Epi& E) {
;     ...
;             PG8_WAIT_V(6); PG8_BAR; PG8_MMA(1, 1, At, B1); PG8_BAR;
;             PG8_LDB(B0, 1, 0); PG8_SCHED; PG8_LDA(At, 1, 0); PG8_STAGE(PG8_SA(0, 1), a2 + hstepA, voffA);
;             PG8_WAIT_L(8); PG8_BAR; PG8_WAIT_L(0); PG8_MMA(0, 0, At, B0); PG8_BAR; PG8_SCHED;
;             PG8_LDB(B1, 1, 1); PG8_STAGE(PG8_SB(1, 0), b3, voffB);
;             PG8_BAR; PG8_WAIT_L(0); PG8_MMA(0, 1, At, B1); PG8_BAR;
;             PG8_LDA(At, 1, 1); PG8_STAGE(PG8_SA(1, 0), a3, voffA);
;             PG8_BAR; PG8_WAIT_L(0); PG8_MMA(1, 0, At, B0); PG8_BAR; PG8_SCHED;
	s_mov_b32 m0, vcc_lo
	global_load_lds_dwordx4 v188, s[72:73]
	s_mov_b32 m0, s43
	s_nop 0
	global_load_lds_dwordx4 v192, s[72:73]
	s_waitcnt vmcnt(6)
	s_barrier
	s_setprio 1
	v_mfma_f32_16x16x32_bf16 v[40:43], v[176:179], v[124:127], v[40:43]
	v_mfma_f32_16x16x32_bf16 v[44:47], v[196:199], v[124:127], v[44:47]
	v_mfma_f32_16x16x32_bf16 v[16:19], v[176:179], v[140:143], v[16:19]
	v_mfma_f32_16x16x32_bf16 v[20:23], v[196:199], v[140:143], v[20:23]
	v_mfma_f32_16x16x32_bf16 v[0:3], v[176:179], v[156:159], v[0:3]
	v_mfma_f32_16x16x32_bf16 v[4:7], v[196:199], v[156:159], v[4:7]
	v_mfma_f32_16x16x32_bf16 v[32:35], v[176:179], v[116:119], v[80:83]
	v_mfma_f32_16x16x32_bf16 v[36:39], v[196:199], v[116:119], v[84:87]
	v_mfma_f32_16x16x32_bf16 v[40:43], v[180:183], v[136:139], v[40:43]
	v_mfma_f32_16x16x32_bf16 v[44:47], v[200:203], v[136:139], v[44:47]
	v_mfma_f32_16x16x32_bf16 v[16:19], v[180:183], v[144:147], v[16:19]
	v_mfma_f32_16x16x32_bf16 v[20:23], v[200:203], v[144:147], v[20:23]
	v_mfma_f32_16x16x32_bf16 v[0:3], v[180:183], v[164:167], v[0:3]
	v_mfma_f32_16x16x32_bf16 v[4:7], v[200:203], v[164:167], v[4:7]
	v_mfma_f32_16x16x32_bf16 v[32:35], v[180:183], v[120:123], v[32:35]
	v_mfma_f32_16x16x32_bf16 v[36:39], v[200:203], v[120:123], v[36:39]
	s_setprio 0
	v_add_u32_e32 v84, s90, v219
	s_barrier
	ds_read_b128 v[48:51], v84
	ds_read_b128 v[52:55], v84 offset:1024
	ds_read_b128 v[80:83], v84 offset:2048
	ds_read_b128 v[84:87], v84 offset:3072
	s_mov_b32 m0, s96
	ds_read_b128 v[116:119], v227 offset:32768
	ds_read_b128 v[120:123], v227 offset:33792
	ds_read_b128 v[124:127], v227 offset:34816
	ds_read_b128 v[136:139], v227 offset:35840
	ds_read_b128 v[156:159], v227 offset:36864
	ds_read_b128 v[176:179], v227 offset:37888
	ds_read_b128 v[180:183], v227 offset:38912
	ds_read_b128 v[196:199], v227 offset:39936
	global_load_lds_dwordx4 v186, s[70:71]
	s_mov_b32 m0, s97
	s_nop 0
	global_load_lds_dwordx4 v190, s[70:71]
	s_waitcnt lgkmcnt(8)
	s_barrier
	s_waitcnt lgkmcnt(0)
	s_setprio 1
	s_waitcnt lgkmcnt(0)
	v_mfma_f32_16x16x32_bf16 v[140:143], v[48:51], v[116:119], v[172:175]
	v_mfma_f32_16x16x32_bf16 v[172:175], v[52:55], v[120:123], v[140:143]
	v_mfma_f32_16x16x32_bf16 v[140:143], v[80:83], v[116:119], v[168:171]
	v_mfma_f32_16x16x32_bf16 v[168:171], v[84:87], v[120:123], v[140:143]
	v_mfma_f32_16x16x32_bf16 v[140:143], v[48:51], v[124:127], v[152:155]
	v_mfma_f32_16x16x32_bf16 v[152:155], v[52:55], v[136:139], v[140:143]
	v_mfma_f32_16x16x32_bf16 v[140:143], v[80:83], v[124:127], v[148:151]
	v_mfma_f32_16x16x32_bf16 v[132:135], v[48:51], v[156:159], v[132:135]
	v_mfma_f32_16x16x32_bf16 v[128:131], v[80:83], v[156:159], v[128:131]
	v_mfma_f32_16x16x32_bf16 v[112:115], v[48:51], v[180:183], v[112:115]
	v_mfma_f32_16x16x32_bf16 v[108:111], v[80:83], v[180:183], v[108:111]
	v_mfma_f32_16x16x32_bf16 v[148:151], v[84:87], v[136:139], v[140:143]
	v_mfma_f32_16x16x32_bf16 v[132:135], v[52:55], v[176:179], v[132:135]
	v_mfma_f32_16x16x32_bf16 v[128:131], v[84:87], v[176:179], v[128:131]
	v_mfma_f32_16x16x32_bf16 v[112:115], v[52:55], v[196:199], v[112:115]
	v_mfma_f32_16x16x32_bf16 v[108:111], v[84:87], v[196:199], v[108:111]
	s_setprio 0
	s_barrier
	v_add_u32_e32 v140, s91, v219
	s_mov_b32 m0, s19
	ds_read_b128 v[200:203], v140
	ds_read_b128 v[204:207], v140 offset:1024
	ds_read_b128 v[222:225], v140 offset:2048
	ds_read_b128 v[234:237], v140 offset:3072
	global_load_lds_dwordx4 v188, s[100:101]
	s_mov_b32 m0, s15
	s_nop 0
	global_load_lds_dwordx4 v192, s[100:101]
	s_barrier
	s_waitcnt lgkmcnt(0)
	s_setprio 1
	s_waitcnt lgkmcnt(0)
	v_mfma_f32_16x16x32_bf16 v[56:59], v[222:225], v[116:119], v[56:59]
	v_mfma_f32_16x16x32_bf16 v[140:143], v[200:203], v[116:119], v[160:163]
	v_mfma_f32_16x16x32_bf16 v[164:167], v[234:237], v[120:123], v[56:59]
	v_mfma_f32_16x16x32_bf16 v[56:59], v[200:203], v[124:127], v[64:67]
	v_mfma_f32_16x16x32_bf16 v[160:163], v[204:207], v[120:123], v[140:143]
	v_mfma_f32_16x16x32_bf16 v[140:143], v[204:207], v[136:139], v[56:59]
	v_mfma_f32_16x16x32_bf16 v[56:59], v[222:225], v[124:127], v[68:71]
	v_mfma_f32_16x16x32_bf16 v[144:147], v[234:237], v[136:139], v[56:59]
	v_mfma_f32_16x16x32_bf16 v[56:59], v[200:203], v[156:159], v[76:79]
	v_mfma_f32_16x16x32_bf16 v[120:123], v[204:207], v[176:179], v[56:59]
	v_mfma_f32_16x16x32_bf16 v[56:59], v[222:225], v[156:159], v[96:99]
	v_mfma_f32_16x16x32_bf16 v[124:127], v[234:237], v[176:179], v[56:59]
	v_mfma_f32_16x16x32_bf16 v[56:59], v[200:203], v[180:183], v[100:103]
	v_mfma_f32_16x16x32_bf16 v[100:103], v[204:207], v[196:199], v[56:59]
	v_mfma_f32_16x16x32_bf16 v[56:59], v[222:225], v[180:183], v[104:107]
	v_mfma_f32_16x16x32_bf16 v[104:107], v[234:237], v[196:199], v[56:59]
	s_setprio 0
	s_mov_b32 m0, s16
	s_barrier
	s_nop 2
	ds_read_b128 v[56:59], v227 offset:49152
	ds_read_b128 v[64:67], v227 offset:50176
	ds_read_b128 v[68:71], v227 offset:51200
	ds_read_b128 v[76:79], v227 offset:52224
	ds_read_b128 v[96:99], v227 offset:53248
	ds_read_b128 v[116:119], v227 offset:54272
	ds_read_b128 v[136:139], v227 offset:55296
	ds_read_b128 v[156:159], v227 offset:56320
	global_load_lds_dwordx4 v186, s[98:99]
	s_mov_b32 m0, s17
	s_nop 0
	global_load_lds_dwordx4 v190, s[98:99]
	s_barrier
; #define PG8_STAGE(bufoff, gbase, voff) do { _Pragma("unroll") for (int _i = 0; _i < 2; ++_i) \
;         __builtin_amdgcn_global_load_lds((const unsigned*)((const char*)(gbase) + (voff)[_i]), (LAS unsigned*)(lds + (bufoff) + ldsw + _i * 8192), 16, 0, 0); } while (0)
; #define PG8_MMA(ai, bj, At, Bt) do { __builtin_amdgcn_s_setprio(1); _Pragma("unroll") for (int m = 0; m < 4; ++m) _Pragma("unroll") for (int n = 0; n < 2; ++n) _Pragma("unroll") for (int k = 0; k < 2; ++k) \
;         acc[ai][bj][m][n] = __builtin_amdgcn_mfma_f32_16x16x32_bf16(Bt[n][k], At[m][k], acc[ai][bj][m][n], 0, 0, 0); __builtin_amdgcn_s_setprio(0); } while (0)
; #define PG8_WAIT_V(n) asm volatile("s_waitcnt vmcnt(" #n ")" ::: "memory")
; #define PG8_WAIT_L(n) asm volatile("s_waitcnt lgkmcnt(" #n ")" ::: "memory")
; #define PG8_BAR __builtin_amdgcn_s_barrier()
; #define PG8_SCHED __builtin_amdgcn_sched_barrier(0)
; template <class Epi, class S_t>
; __device__ __forceinline__ void gemm_phase(LAS unsigned char* lds, int lda, int ldb, const S_t& S, const Epi& E) {
;     ...
;             PG8_BAR; PG8_WAIT_L(0); PG8_MMA(1, 0, At, B0); PG8_BAR; PG8_SCHED;
;             PG8_STAGE(PG8_SB(1, 1), b3 + hstepB, voffB);
;             PG8_WAIT_V(6); PG8_BAR; PG8_MMA(1, 1, At, B1); PG8_BAR;
;     __device__ __forceinline__ void operator()(const f32x4 (&acc)[2][2][4][2], const Unit& u, int wr, int wc, int fr, int fq) const {
;         const int row0 = u.pm * BM + wr * 64 + fr, ch0 = u.pn * HALF + wc * 32 + 8 * fq;
;         float br[8], bi[8], sp[8];
; #pragma unroll
;         for (int q = 0; q < 2; ++q) { const f32x4 a = *(const f32x4*)(brg + ch0 + 4 * q), b = *(const f32x4*)(big + ch0 + 4 * q), c = *(const f32x4*)(spl + ch0 + 4 * q);
; #pragma unroll
;             for (int j = 0; j < 4; ++j) { br[4 * q + j] = a[j]; bi[4 * q + j] = b[j]; sp[4 * q + j] = c[j]; } }
;         u32x4 xraw[2][4];
; #pragma unroll
;         for (int ai = 0; ai < 2; ++ai)
; #pragma unroll
;             for (int m = 0; m < 4; ++m) xraw[ai][m] = *(const u32x4*)(XC + (size_t)(row0 + ai * HALF + m * 16) * LW + ch0);
	s_waitcnt lgkmcnt(0)
	s_setprio 1
	s_waitcnt lgkmcnt(0)
	v_mfma_f32_16x16x32_bf16 v[92:95], v[48:51], v[56:59], v[92:95]
	v_mfma_f32_16x16x32_bf16 v[88:91], v[80:83], v[56:59], v[88:91]
	v_mfma_f32_16x16x32_bf16 v[72:75], v[48:51], v[68:71], v[72:75]
	v_mfma_f32_16x16x32_bf16 v[60:63], v[80:83], v[68:71], v[60:63]
	v_mfma_f32_16x16x32_bf16 v[28:31], v[48:51], v[96:99], v[28:31]
	v_mfma_f32_16x16x32_bf16 v[24:27], v[80:83], v[96:99], v[24:27]
	v_mfma_f32_16x16x32_bf16 v[12:15], v[48:51], v[136:139], v[12:15]
	v_mfma_f32_16x16x32_bf16 v[8:11], v[80:83], v[136:139], v[8:11]
	v_mfma_f32_16x16x32_bf16 v[92:95], v[52:55], v[64:67], v[92:95]
	v_mfma_f32_16x16x32_bf16 v[88:91], v[84:87], v[64:67], v[88:91]
	v_mfma_f32_16x16x32_bf16 v[72:75], v[52:55], v[76:79], v[72:75]
	v_mfma_f32_16x16x32_bf16 v[60:63], v[84:87], v[76:79], v[60:63]
	v_mfma_f32_16x16x32_bf16 v[28:31], v[52:55], v[116:119], v[28:31]
	v_mfma_f32_16x16x32_bf16 v[24:27], v[84:87], v[116:119], v[24:27]
	v_mfma_f32_16x16x32_bf16 v[12:15], v[52:55], v[156:159], v[12:15]
	v_mfma_f32_16x16x32_bf16 v[8:11], v[84:87], v[156:159], v[8:11]
	s_setprio 0
	s_barrier
	s_mov_b32 m0, s1
	global_load_lds_dwordx4 v188, s[68:69]
	s_mov_b32 m0, s0
	s_nop 0
	global_load_lds_dwordx4 v192, s[68:69]
	s_waitcnt vmcnt(6)
	s_barrier
	s_setprio 1
	v_mfma_f32_16x16x32_bf16 v[32:35], v[200:203], v[56:59], v[32:35]
	v_mfma_f32_16x16x32_bf16 v[80:83], v[204:207], v[64:67], v[32:35]
	v_mfma_f32_16x16x32_bf16 v[32:35], v[222:225], v[56:59], v[36:39]
	v_mfma_f32_16x16x32_bf16 v[84:87], v[234:237], v[64:67], v[32:35]
	v_mfma_f32_16x16x32_bf16 v[32:35], v[200:203], v[68:71], v[40:43]
	v_mfma_f32_16x16x32_bf16 v[40:43], v[204:207], v[76:79], v[32:35]
	v_mfma_f32_16x16x32_bf16 v[32:35], v[222:225], v[68:71], v[44:47]
	v_mfma_f32_16x16x32_bf16 v[16:19], v[200:203], v[96:99], v[16:19]
	v_mfma_f32_16x16x32_bf16 v[20:23], v[222:225], v[96:99], v[20:23]
	v_mfma_f32_16x16x32_bf16 v[0:3], v[200:203], v[136:139], v[0:3]
	v_mfma_f32_16x16x32_bf16 v[4:7], v[222:225], v[136:139], v[4:7]
	v_mfma_f32_16x16x32_bf16 v[44:47], v[234:237], v[76:79], v[32:35]
	v_mfma_f32_16x16x32_bf16 v[16:19], v[204:207], v[116:119], v[16:19]
	v_mfma_f32_16x16x32_bf16 v[20:23], v[234:237], v[116:119], v[20:23]
	v_mfma_f32_16x16x32_bf16 v[0:3], v[204:207], v[156:159], v[0:3]
	v_mfma_f32_16x16x32_bf16 v[4:7], v[234:237], v[156:159], v[4:7]
	s_setprio 0
	s_movk_i32 s0, 0x100
	s_andn2_b64 vcc, exec, s[66:67]
	s_mov_b64 s[68:69], -1
	s_mov_b64 s[66:67], 0
	s_barrier
	s_cbranch_vccz .LBB0_547
	v_lshl_or_b32 v196, s42, 7, v221
	v_readlane_b32 s68, v254, 49
	v_ashrrev_i32_e32 v197, 31, v196
	v_readlane_b32 s76, v254, 57
	v_readlane_b32 s77, v254, 58
	v_lshlrev_b64 v[32:33], 2, v[196:197]
	v_readlane_b32 s80, v254, 61
	v_readlane_b32 s81, v254, 62
	s_mov_b64 s[24:25], s[76:77]
	s_mov_b64 s[28:29], s[80:81]
	v_lshl_add_u64 v[34:35], s[24:25], 0, v[32:33]
	v_lshl_add_u64 v[48:49], s[28:29], 0, v[32:33]
	v_lshl_add_u64 v[50:51], s[10:11], 0, v[32:33]
	global_load_dwordx4 v[56:59], v[34:35], off offset:16
	global_load_dwordx4 v[68:71], v[34:35], off
	global_load_dwordx4 v[36:39], v[48:49], off offset:16
	s_nop 0
	global_load_dwordx4 v[32:35], v[48:49], off
	global_load_dwordx4 v[52:55], v[50:51], off offset:16
	global_load_dwordx4 v[64:67], v[50:51], off
	v_lshl_add_u32 v224, s5, 8, v215
	v_or_b32_e32 v222, 16, v224
	v_ashrrev_i32_e32 v225, 31, v224
	v_ashrrev_i32_e32 v223, 31, v222
	v_lshl_add_u64 v[48:49], v[196:197], 1, s[8:9]
	v_lshlrev_b64 v[50:51], 12, v[224:225]
	v_lshlrev_b64 v[76:77], 12, v[222:223]
	v_or_b32_e32 v208, 32, v224
	v_or_b32_e32 v206, 48, v224
	v_lshl_add_u64 v[50:51], v[48:49], 0, v[50:51]
	v_lshl_add_u64 v[76:77], v[48:49], 0, v[76:77]
	v_ashrrev_i32_e32 v209, 31, v208
	v_ashrrev_i32_e32 v207, 31, v206
	global_load_dwordx4 v[180:183], v[50:51], off
	global_load_dwordx4 v[176:179], v[76:77], off
	v_lshlrev_b64 v[50:51], 12, v[208:209]
	v_lshlrev_b64 v[76:77], 12, v[206:207]
	v_add_u32_e32 v204, 0x80, v224
	v_add_u32_e32 v202, 0x90, v224
	v_lshl_add_u64 v[50:51], v[48:49], 0, v[50:51]
	v_lshl_add_u64 v[76:77], v[48:49], 0, v[76:77]
	v_ashrrev_i32_e32 v205, 31, v204
	v_ashrrev_i32_e32 v203, 31, v202
	global_load_dwordx4 v[156:159], v[50:51], off
	global_load_dwordx4 v[136:139], v[76:77], off
	v_lshlrev_b64 v[50:51], 12, v[204:205]
	v_lshlrev_b64 v[76:77], 12, v[202:203]
	v_add_u32_e32 v200, 0xa0, v224
	v_add_u32_e32 v198, 0xb0, v224
	v_lshl_add_u64 v[50:51], v[48:49], 0, v[50:51]
	v_lshl_add_u64 v[76:77], v[48:49], 0, v[76:77]
	v_ashrrev_i32_e32 v201, 31, v200
	v_ashrrev_i32_e32 v199, 31, v198
	global_load_dwordx4 v[116:119], v[50:51], off
	global_load_dwordx4 v[96:99], v[76:77], off
	v_lshlrev_b64 v[50:51], 12, v[200:201]
	v_lshlrev_b64 v[76:77], 12, v[198:199]
	v_lshl_add_u64 v[50:51], v[48:49], 0, v[50:51]
	v_lshl_add_u64 v[48:49], v[48:49], 0, v[76:77]
	global_load_dwordx4 v[76:79], v[50:51], off
	s_nop 0
	global_load_dwordx4 v[48:51], v[48:49], off
	v_readlane_b32 s69, v254, 50
	v_readlane_b32 s70, v254, 51
	v_readlane_b32 s71, v254, 52
	v_readlane_b32 s72, v254, 53
	v_readlane_b32 s73, v254, 54
	v_readlane_b32 s74, v254, 55
	v_readlane_b32 s75, v254, 56
	v_readlane_b32 s78, v254, 59
	v_readlane_b32 s79, v254, 60
	v_readlane_b32 s82, v254, 63
	v_readlane_b32 s83, v255, 0
	s_waitcnt vmcnt(0)
; __device__ __forceinline__ unsigned pk2(float lo, float hi) { unsigned r; asm("v_cvt_pk_bf16_f32 %0, %1, %2" : "=v"(r) : "v"(lo), "v"(hi)); return r; }
; __device__ __forceinline__ float sigmoidf_(float x) { return __builtin_amdgcn_rcpf(1.0f + __expf(-x)); }
;     __device__ __forceinline__ void operator()(const f32x4 (&acc)[2][2][4][2], const Unit& u, int wr, int wc, int fr, int fq) const {
;     ...
;         for (int ai = 0; ai < 2; ++ai)
; #pragma unroll
;             for (int m = 0; m < 4; ++m) { const size_t off = (size_t)(row0 + ai * HALF + m * 16) * LW + ch0;
;                 float xc[8]; unpack8(xraw[ai][m], xc);
;                 float la[8], uu[8];
; #pragma unroll
;                 for (int n = 0; n < 2; ++n)
; #pragma unroll
;                     for (int j = 0; j < 4; ++j) { const int e = 4 * n + j;
;                         const float r = sigmoidf_(acc[ai][0][m][n][j] + br[e]), ig = sigmoidf_(acc[ai][1][m][n][j] + bi[e]);
;                         const float l = -8.0f * r * sp[e]; la[e] = l;
;                         const float x2 = 2.0f * l;
;                         const float om = x2 > -0.03125f ? -x2 * (1.0f + x2 * (0.5f + x2 * (0.16666667f + x2 * 0.041666668f))) : 1.0f - __expf(x2);
;                         uu[e] = __builtin_amdgcn_sqrtf(om) * (ig * xc[e]); }
;                 u32x4 w0, w1; w0.x = pk2(la[0], uu[0]); w0.y = pk2(la[1], uu[1]); w0.z = pk2(la[2], uu[2]); w0.w = pk2(la[3], uu[3]);
;                 w1.x = pk2(la[4], uu[4]); w1.y = pk2(la[5], uu[5]); w1.z = pk2(la[6], uu[6]); w1.w = pk2(la[7], uu[7]);
;                 *(u32x4*)(LU + off) = w0; *(u32x4*)(LU + off + 4) = w1; }
	s_mov_b32 s68, 0xbfb8aa3b
	s_mov_b32 s69, 0xbfb8aa3b
	s_mov_b32 s70, 0x3fb8aa3b
	s_mov_b32 s71, 0x3fb8aa3b
	s_mov_b32 s72, 1.0
	s_mov_b32 s73, 1.0
	s_mov_b32 s74, 0x3d2aaaab
	s_mov_b32 s75, 0x3d2aaaab
	s_mov_b32 s76, 0.5
	s_mov_b32 s77, 0.5
	v_mov_b32_e32 v222, v229
	v_mov_b32_e32 v223, v229
	v_mul_f32_e32 v64, 0xc1000000, v64
	v_mul_f32_e32 v65, 0xc1000000, v65
	v_mul_f32_e32 v66, 0xc1000000, v66
	v_mul_f32_e32 v67, 0xc1000000, v67
	v_mul_f32_e32 v52, 0xc1000000, v52
	v_mul_f32_e32 v53, 0xc1000000, v53
	v_mul_f32_e32 v54, 0xc1000000, v54
	v_mul_f32_e32 v55, 0xc1000000, v55
	v_lshlrev_b32_e32 v225, 13, v224
	v_lshl_add_u32 v225, v196, 2, v225
	v_pk_add_f32 v[172:173], v[172:173], v[68:69]
	v_pk_add_f32 v[160:161], v[160:161], v[32:33]
	v_pk_add_f32 v[174:175], v[174:175], v[70:71]
	v_pk_add_f32 v[162:163], v[162:163], v[34:35]
	v_pk_add_f32 v[168:169], v[168:169], v[56:57]
	v_pk_add_f32 v[164:165], v[164:165], v[36:37]
	v_pk_add_f32 v[170:171], v[170:171], v[58:59]
	v_pk_add_f32 v[166:167], v[166:167], v[38:39]
	v_pk_mul_f32 v[172:173], v[172:173], s[68:69]
	v_pk_mul_f32 v[160:161], v[160:161], s[68:69]
	v_pk_mul_f32 v[174:175], v[174:175], s[68:69]
	v_pk_mul_f32 v[162:163], v[162:163], s[68:69]
	v_pk_mul_f32 v[168:169], v[168:169], s[68:69]
	v_pk_mul_f32 v[164:165], v[164:165], s[68:69]
	v_pk_mul_f32 v[170:171], v[170:171], s[68:69]
	v_pk_mul_f32 v[166:167], v[166:167], s[68:69]
	v_exp_f32_e32 v172, v172
	v_exp_f32_e32 v173, v173
	v_exp_f32_e32 v174, v174
	v_exp_f32_e32 v175, v175
	v_exp_f32_e32 v168, v168
	v_exp_f32_e32 v169, v169
	v_exp_f32_e32 v170, v170
	v_exp_f32_e32 v171, v171
	v_exp_f32_e32 v160, v160
	v_exp_f32_e32 v161, v161
	v_exp_f32_e32 v162, v162
	v_exp_f32_e32 v163, v163
	v_exp_f32_e32 v164, v164
	v_exp_f32_e32 v165, v165
	v_exp_f32_e32 v166, v166
	v_exp_f32_e32 v167, v167
	v_pk_add_f32 v[172:173], v[172:173], s[72:73]
	v_pk_add_f32 v[160:161], v[160:161], s[72:73]
	v_pk_add_f32 v[174:175], v[174:175], s[72:73]
	v_pk_add_f32 v[162:163], v[162:163], s[72:73]
	v_pk_add_f32 v[168:169], v[168:169], s[72:73]
	v_pk_add_f32 v[164:165], v[164:165], s[72:73]
	v_pk_add_f32 v[170:171], v[170:171], s[72:73]
	v_pk_add_f32 v[166:167], v[166:167], s[72:73]
	v_rcp_f32_e32 v172, v172
	v_rcp_f32_e32 v173, v173
	v_rcp_f32_e32 v174, v174
	v_rcp_f32_e32 v175, v175
	v_rcp_f32_e32 v168, v168
	v_rcp_f32_e32 v169, v169
	v_rcp_f32_e32 v170, v170
	v_rcp_f32_e32 v171, v171
	v_rcp_f32_e32 v160, v160
	v_rcp_f32_e32 v161, v161
	v_rcp_f32_e32 v162, v162
	v_rcp_f32_e32 v163, v163
	v_rcp_f32_e32 v164, v164
	v_rcp_f32_e32 v165, v165
	v_rcp_f32_e32 v166, v166
	v_rcp_f32_e32 v167, v167
	v_lshlrev_b32_e32 v230, 16, v180
	v_and_b32_e32 v231, 0xffff0000, v180
	v_lshlrev_b32_e32 v234, 16, v181
	v_and_b32_e32 v235, 0xffff0000, v181
	v_lshlrev_b32_e32 v236, 16, v182
	v_and_b32_e32 v237, 0xffff0000, v182
	v_lshlrev_b32_e32 v238, 16, v183
	v_and_b32_e32 v239, 0xffff0000, v183
	v_pk_mul_f32 v[172:173], v[64:65], v[172:173]
	v_pk_mul_f32 v[174:175], v[66:67], v[174:175]
	v_pk_mul_f32 v[168:169], v[52:53], v[168:169]
	v_pk_mul_f32 v[170:171], v[54:55], v[170:171]
	v_pk_mul_f32 v[160:161], v[160:161], v[230:231]
	v_pk_mul_f32 v[162:163], v[162:163], v[234:235]
	v_pk_mul_f32 v[164:165], v[164:165], v[236:237]
	v_pk_mul_f32 v[166:167], v[166:167], v[238:239]
	v_pk_add_f32 v[198:199], v[172:173], v[172:173]
	v_pk_add_f32 v[200:201], v[174:175], v[174:175]
	v_pk_mul_f32 v[206:207], v[198:199], s[70:71]
	v_pk_mul_f32 v[208:209], v[200:201], s[70:71]
	v_pk_fma_f32 v[202:203], v[198:199], s[74:75], v[222:223]
	v_pk_fma_f32 v[204:205], v[200:201], s[74:75], v[222:223]
	v_exp_f32_e32 v206, v206
	v_exp_f32_e32 v207, v207
	v_exp_f32_e32 v208, v208
	v_exp_f32_e32 v209, v209
	v_pk_fma_f32 v[202:203], v[198:199], v[202:203], s[76:77]
	v_pk_fma_f32 v[204:205], v[200:201], v[204:205], s[76:77]
	v_pk_fma_f32 v[202:203], v[198:199], v[202:203], s[72:73]
	v_pk_fma_f32 v[204:205], v[200:201], v[204:205], s[72:73]
	v_pk_mul_f32 v[202:203], v[202:203], v[198:199] neg_lo:[0,1] neg_hi:[0,1]
	v_pk_mul_f32 v[204:205], v[204:205], v[200:201] neg_lo:[0,1] neg_hi:[0,1]
	v_pk_add_f32 v[206:207], s[72:73], v[206:207] neg_lo:[0,1] neg_hi:[0,1]
	v_pk_add_f32 v[208:209], s[72:73], v[208:209] neg_lo:[0,1] neg_hi:[0,1]
	v_cmp_lt_f32_e64 s[78:79], s4, v198
	v_cmp_lt_f32_e64 s[80:81], s4, v199
	v_cmp_lt_f32_e64 s[82:83], s4, v200
	v_cmp_lt_f32_e64 s[24:25], s4, v201
	v_cndmask_b32_e64 v202, v206, v202, s[78:79]
	v_cndmask_b32_e64 v203, v207, v203, s[80:81]
	v_cndmask_b32_e64 v204, v208, v204, s[82:83]
	v_cndmask_b32_e64 v205, v209, v205, s[24:25]
	v_sqrt_f32_e32 v202, v202
	v_sqrt_f32_e32 v203, v203
	v_sqrt_f32_e32 v204, v204
	v_sqrt_f32_e32 v205, v205
	v_pk_mul_f32 v[160:161], v[160:161], v[202:203]
	v_pk_mul_f32 v[162:163], v[162:163], v[204:205]
	v_pk_add_f32 v[198:199], v[168:169], v[168:169]
	v_pk_add_f32 v[200:201], v[170:171], v[170:171]
	v_pk_mul_f32 v[206:207], v[198:199], s[70:71]
	v_pk_mul_f32 v[208:209], v[200:201], s[70:71]
	v_pk_fma_f32 v[202:203], v[198:199], s[74:75], v[222:223]
	v_pk_fma_f32 v[204:205], v[200:201], s[74:75], v[222:223]
	v_exp_f32_e32 v206, v206
	v_exp_f32_e32 v207, v207
	v_exp_f32_e32 v208, v208
	v_exp_f32_e32 v209, v209
	v_pk_fma_f32 v[202:203], v[198:199], v[202:203], s[76:77]
	v_pk_fma_f32 v[204:205], v[200:201], v[204:205], s[76:77]
	v_pk_fma_f32 v[202:203], v[198:199], v[202:203], s[72:73]
	v_pk_fma_f32 v[204:205], v[200:201], v[204:205], s[72:73]
	v_pk_mul_f32 v[202:203], v[202:203], v[198:199] neg_lo:[0,1] neg_hi:[0,1]
	v_pk_mul_f32 v[204:205], v[204:205], v[200:201] neg_lo:[0,1] neg_hi:[0,1]
	v_pk_add_f32 v[206:207], s[72:73], v[206:207] neg_lo:[0,1] neg_hi:[0,1]
; __device__ __forceinline__ unsigned pk2(float lo, float hi) { unsigned r; asm("v_cvt_pk_bf16_f32 %0, %1, %2" : "=v"(r) : "v"(lo), "v"(hi)); return r; }
; __device__ __forceinline__ float sigmoidf_(float x) { return __builtin_amdgcn_rcpf(1.0f + __expf(-x)); }
;     __device__ __forceinline__ void operator()(const f32x4 (&acc)[2][2][4][2], const Unit& u, int wr, int wc, int fr, int fq) const {
;     ...
;         for (int ai = 0; ai < 2; ++ai)
; #pragma unroll
;             for (int m = 0; m < 4; ++m) { const size_t off = (size_t)(row0 + ai * HALF + m * 16) * LW + ch0;
;                 float xc[8]; unpack8(xraw[ai][m], xc);
;                 float la[8], uu[8];
; #pragma unroll
;                 for (int n = 0; n < 2; ++n)
; #pragma unroll
;                     for (int j = 0; j < 4; ++j) { const int e = 4 * n + j;
;                         const float r = sigmoidf_(acc[ai][0][m][n][j] + br[e]), ig = sigmoidf_(acc[ai][1][m][n][j] + bi[e]);
;                         const float l = -8.0f * r * sp[e]; la[e] = l;
;                         const float x2 = 2.0f * l;
;                         const float om = x2 > -0.03125f ? -x2 * (1.0f + x2 * (0.5f + x2 * (0.16666667f + x2 * 0.041666668f))) : 1.0f - __expf(x2);
;                         uu[e] = __builtin_amdgcn_sqrtf(om) * (ig * xc[e]); }
;                 u32x4 w0, w1; w0.x = pk2(la[0], uu[0]); w0.y = pk2(la[1], uu[1]); w0.z = pk2(la[2], uu[2]); w0.w = pk2(la[3], uu[3]);
;                 w1.x = pk2(la[4], uu[4]); w1.y = pk2(la[5], uu[5]); w1.z = pk2(la[6], uu[6]); w1.w = pk2(la[7], uu[7]);
;                 *(u32x4*)(LU + off) = w0; *(u32x4*)(LU + off + 4) = w1; }
	v_pk_add_f32 v[208:209], s[72:73], v[208:209] neg_lo:[0,1] neg_hi:[0,1]
	v_cmp_lt_f32_e64 s[78:79], s4, v198
	v_cmp_lt_f32_e64 s[80:81], s4, v199
	v_cmp_lt_f32_e64 s[82:83], s4, v200
	v_cmp_lt_f32_e64 s[24:25], s4, v201
	v_cndmask_b32_e64 v202, v206, v202, s[78:79]
	v_cndmask_b32_e64 v203, v207, v203, s[80:81]
	v_cndmask_b32_e64 v204, v208, v204, s[82:83]
	v_cndmask_b32_e64 v205, v209, v205, s[24:25]
	v_sqrt_f32_e32 v202, v202
	v_sqrt_f32_e32 v203, v203
	v_sqrt_f32_e32 v204, v204
	v_sqrt_f32_e32 v205, v205
	v_pk_mul_f32 v[164:165], v[164:165], v[202:203]
	v_pk_mul_f32 v[166:167], v[166:167], v[204:205]
	v_cvt_pk_bf16_f32 v160, v172, v160
	v_cvt_pk_bf16_f32 v161, v173, v161
	v_cvt_pk_bf16_f32 v162, v174, v162
	v_cvt_pk_bf16_f32 v163, v175, v163
	v_cvt_pk_bf16_f32 v164, v168, v164
	v_cvt_pk_bf16_f32 v165, v169, v165
	v_cvt_pk_bf16_f32 v166, v170, v166
	v_cvt_pk_bf16_f32 v167, v171, v167
	v_mov_b32_e32 v197, v225
	global_store_dwordx4 v197, v[160:163], s[44:45]
	global_store_dwordx4 v197, v[164:167], s[44:45] offset:16
	v_pk_add_f32 v[152:153], v[152:153], v[68:69]
	v_pk_add_f32 v[140:141], v[140:141], v[32:33]
	v_pk_add_f32 v[154:155], v[154:155], v[70:71]
	v_pk_add_f32 v[142:143], v[142:143], v[34:35]
	v_pk_add_f32 v[148:149], v[148:149], v[56:57]
	v_pk_add_f32 v[144:145], v[144:145], v[36:37]
	v_pk_add_f32 v[150:151], v[150:151], v[58:59]
	v_pk_add_f32 v[146:147], v[146:147], v[38:39]
	v_pk_mul_f32 v[152:153], v[152:153], s[68:69]
	v_pk_mul_f32 v[140:141], v[140:141], s[68:69]
	v_pk_mul_f32 v[154:155], v[154:155], s[68:69]
	v_pk_mul_f32 v[142:143], v[142:143], s[68:69]
	v_pk_mul_f32 v[148:149], v[148:149], s[68:69]
	v_pk_mul_f32 v[144:145], v[144:145], s[68:69]
	v_pk_mul_f32 v[150:151], v[150:151], s[68:69]
	v_pk_mul_f32 v[146:147], v[146:147], s[68:69]
	v_exp_f32_e32 v152, v152
	v_exp_f32_e32 v153, v153
	v_exp_f32_e32 v154, v154
	v_exp_f32_e32 v155, v155
	v_exp_f32_e32 v148, v148
	v_exp_f32_e32 v149, v149
	v_exp_f32_e32 v150, v150
	v_exp_f32_e32 v151, v151
	v_exp_f32_e32 v140, v140
	v_exp_f32_e32 v141, v141
	v_exp_f32_e32 v142, v142
	v_exp_f32_e32 v143, v143
	v_exp_f32_e32 v144, v144
	v_exp_f32_e32 v145, v145
	v_exp_f32_e32 v146, v146
	v_exp_f32_e32 v147, v147
	v_pk_add_f32 v[152:153], v[152:153], s[72:73]
	v_pk_add_f32 v[140:141], v[140:141], s[72:73]
	v_pk_add_f32 v[154:155], v[154:155], s[72:73]
	v_pk_add_f32 v[142:143], v[142:143], s[72:73]
	v_pk_add_f32 v[148:149], v[148:149], s[72:73]
	v_pk_add_f32 v[144:145], v[144:145], s[72:73]
	v_pk_add_f32 v[150:151], v[150:151], s[72:73]
	v_pk_add_f32 v[146:147], v[146:147], s[72:73]
	v_rcp_f32_e32 v152, v152
	v_rcp_f32_e32 v153, v153
	v_rcp_f32_e32 v154, v154
	v_rcp_f32_e32 v155, v155
	v_rcp_f32_e32 v148, v148
	v_rcp_f32_e32 v149, v149
	v_rcp_f32_e32 v150, v150
	v_rcp_f32_e32 v151, v151
	v_rcp_f32_e32 v140, v140
	v_rcp_f32_e32 v141, v141
	v_rcp_f32_e32 v142, v142
	v_rcp_f32_e32 v143, v143
	v_rcp_f32_e32 v144, v144
	v_rcp_f32_e32 v145, v145
	v_rcp_f32_e32 v146, v146
	v_rcp_f32_e32 v147, v147
	v_lshlrev_b32_e32 v230, 16, v176
	v_and_b32_e32 v231, 0xffff0000, v176
	v_lshlrev_b32_e32 v234, 16, v177
	v_and_b32_e32 v235, 0xffff0000, v177
	v_lshlrev_b32_e32 v236, 16, v178
	v_and_b32_e32 v237, 0xffff0000, v178
	v_lshlrev_b32_e32 v238, 16, v179
	v_and_b32_e32 v239, 0xffff0000, v179
	v_pk_mul_f32 v[152:153], v[64:65], v[152:153]
	v_pk_mul_f32 v[154:155], v[66:67], v[154:155]
	v_pk_mul_f32 v[148:149], v[52:53], v[148:149]
	v_pk_mul_f32 v[150:151], v[54:55], v[150:151]
	v_pk_mul_f32 v[140:141], v[140:141], v[230:231]
	v_pk_mul_f32 v[142:143], v[142:143], v[234:235]
	v_pk_mul_f32 v[144:145], v[144:145], v[236:237]
	v_pk_mul_f32 v[146:147], v[146:147], v[238:239]
	v_pk_add_f32 v[198:199], v[152:153], v[152:153]
	v_pk_add_f32 v[200:201], v[154:155], v[154:155]
	v_pk_mul_f32 v[206:207], v[198:199], s[70:71]
	v_pk_mul_f32 v[208:209], v[200:201], s[70:71]
	v_pk_fma_f32 v[202:203], v[198:199], s[74:75], v[222:223]
	v_pk_fma_f32 v[204:205], v[200:201], s[74:75], v[222:223]
	v_exp_f32_e32 v206, v206
	v_exp_f32_e32 v207, v207
	v_exp_f32_e32 v208, v208
	v_exp_f32_e32 v209, v209
	v_pk_fma_f32 v[202:203], v[198:199], v[202:203], s[76:77]
	v_pk_fma_f32 v[204:205], v[200:201], v[204:205], s[76:77]
	v_pk_fma_f32 v[202:203], v[198:199], v[202:203], s[72:73]
	v_pk_fma_f32 v[204:205], v[200:201], v[204:205], s[72:73]
	v_pk_mul_f32 v[202:203], v[202:203], v[198:199] neg_lo:[0,1] neg_hi:[0,1]
	v_pk_mul_f32 v[204:205], v[204:205], v[200:201] neg_lo:[0,1] neg_hi:[0,1]
	v_pk_add_f32 v[206:207], s[72:73], v[206:207] neg_lo:[0,1] neg_hi:[0,1]
	v_pk_add_f32 v[208:209], s[72:73], v[208:209] neg_lo:[0,1] neg_hi:[0,1]
	v_cmp_lt_f32_e64 s[78:79], s4, v198
	v_cmp_lt_f32_e64 s[80:81], s4, v199
	v_cmp_lt_f32_e64 s[82:83], s4, v200
	v_cmp_lt_f32_e64 s[24:25], s4, v201
	v_cndmask_b32_e64 v202, v206, v202, s[78:79]
	v_cndmask_b32_e64 v203, v207, v203, s[80:81]
	v_cndmask_b32_e64 v204, v208, v204, s[82:83]
	v_cndmask_b32_e64 v205, v209, v205, s[24:25]
	v_sqrt_f32_e32 v202, v202
	v_sqrt_f32_e32 v203, v203
	v_sqrt_f32_e32 v204, v204
	v_sqrt_f32_e32 v205, v205
	v_pk_mul_f32 v[140:141], v[140:141], v[202:203]
	v_pk_mul_f32 v[142:143], v[142:143], v[204:205]
	v_pk_add_f32 v[198:199], v[148:149], v[148:149]
	v_pk_add_f32 v[200:201], v[150:151], v[150:151]
	v_pk_mul_f32 v[206:207], v[198:199], s[70:71]
	v_pk_mul_f32 v[208:209], v[200:201], s[70:71]
	v_pk_fma_f32 v[202:203], v[198:199], s[74:75], v[222:223]
	v_pk_fma_f32 v[204:205], v[200:201], s[74:75], v[222:223]
	v_exp_f32_e32 v206, v206
	v_exp_f32_e32 v207, v207
	v_exp_f32_e32 v208, v208
	v_exp_f32_e32 v209, v209
	v_pk_fma_f32 v[202:203], v[198:199], v[202:203], s[76:77]
; __device__ __forceinline__ unsigned pk2(float lo, float hi) { unsigned r; asm("v_cvt_pk_bf16_f32 %0, %1, %2" : "=v"(r) : "v"(lo), "v"(hi)); return r; }
; __device__ __forceinline__ float sigmoidf_(float x) { return __builtin_amdgcn_rcpf(1.0f + __expf(-x)); }
;     __device__ __forceinline__ void operator()(const f32x4 (&acc)[2][2][4][2], const Unit& u, int wr, int wc, int fr, int fq) const {
;     ...
;         for (int ai = 0; ai < 2; ++ai)
; #pragma unroll
;             for (int m = 0; m < 4; ++m) { const size_t off = (size_t)(row0 + ai * HALF + m * 16) * LW + ch0;
;                 float xc[8]; unpack8(xraw[ai][m], xc);
;                 float la[8], uu[8];
; #pragma unroll
;                 for (int n = 0; n < 2; ++n)
; #pragma unroll
;                     for (int j = 0; j < 4; ++j) { const int e = 4 * n + j;
;                         const float r = sigmoidf_(acc[ai][0][m][n][j] + br[e]), ig = sigmoidf_(acc[ai][1][m][n][j] + bi[e]);
;                         const float l = -8.0f * r * sp[e]; la[e] = l;
;                         const float x2 = 2.0f * l;
;                         const float om = x2 > -0.03125f ? -x2 * (1.0f + x2 * (0.5f + x2 * (0.16666667f + x2 * 0.041666668f))) : 1.0f - __expf(x2);
;                         uu[e] = __builtin_amdgcn_sqrtf(om) * (ig * xc[e]); }
;                 u32x4 w0, w1; w0.x = pk2(la[0], uu[0]); w0.y = pk2(la[1], uu[1]); w0.z = pk2(la[2], uu[2]); w0.w = pk2(la[3], uu[3]);
;                 w1.x = pk2(la[4], uu[4]); w1.y = pk2(la[5], uu[5]); w1.z = pk2(la[6], uu[6]); w1.w = pk2(la[7], uu[7]);
;                 *(u32x4*)(LU + off) = w0; *(u32x4*)(LU + off + 4) = w1; }
	v_pk_fma_f32 v[204:205], v[200:201], v[204:205], s[76:77]
	v_pk_fma_f32 v[202:203], v[198:199], v[202:203], s[72:73]
	v_pk_fma_f32 v[204:205], v[200:201], v[204:205], s[72:73]
	v_pk_mul_f32 v[202:203], v[202:203], v[198:199] neg_lo:[0,1] neg_hi:[0,1]
	v_pk_mul_f32 v[204:205], v[204:205], v[200:201] neg_lo:[0,1] neg_hi:[0,1]
	v_pk_add_f32 v[206:207], s[72:73], v[206:207] neg_lo:[0,1] neg_hi:[0,1]
	v_pk_add_f32 v[208:209], s[72:73], v[208:209] neg_lo:[0,1] neg_hi:[0,1]
	v_cmp_lt_f32_e64 s[78:79], s4, v198
	v_cmp_lt_f32_e64 s[80:81], s4, v199
	v_cmp_lt_f32_e64 s[82:83], s4, v200
	v_cmp_lt_f32_e64 s[24:25], s4, v201
	v_cndmask_b32_e64 v202, v206, v202, s[78:79]
	v_cndmask_b32_e64 v203, v207, v203, s[80:81]
	v_cndmask_b32_e64 v204, v208, v204, s[82:83]
	v_cndmask_b32_e64 v205, v209, v205, s[24:25]
	v_sqrt_f32_e32 v202, v202
	v_sqrt_f32_e32 v203, v203
	v_sqrt_f32_e32 v204, v204
	v_sqrt_f32_e32 v205, v205
	v_pk_mul_f32 v[144:145], v[144:145], v[202:203]
	v_pk_mul_f32 v[146:147], v[146:147], v[204:205]
	v_cvt_pk_bf16_f32 v140, v152, v140
	v_cvt_pk_bf16_f32 v141, v153, v141
	v_cvt_pk_bf16_f32 v142, v154, v142
	v_cvt_pk_bf16_f32 v143, v155, v143
	v_cvt_pk_bf16_f32 v144, v148, v144
	v_cvt_pk_bf16_f32 v145, v149, v145
	v_cvt_pk_bf16_f32 v146, v150, v146
	v_cvt_pk_bf16_f32 v147, v151, v147
	v_add_u32_e32 v197, 0x20000, v225
	global_store_dwordx4 v197, v[140:143], s[44:45]
	global_store_dwordx4 v197, v[144:147], s[44:45] offset:16
	v_pk_add_f32 v[132:133], v[132:133], v[68:69]
	v_pk_add_f32 v[120:121], v[120:121], v[32:33]
	v_pk_add_f32 v[134:135], v[134:135], v[70:71]
	v_pk_add_f32 v[122:123], v[122:123], v[34:35]
	v_pk_add_f32 v[128:129], v[128:129], v[56:57]
	v_pk_add_f32 v[124:125], v[124:125], v[36:37]
	v_pk_add_f32 v[130:131], v[130:131], v[58:59]
	v_pk_add_f32 v[126:127], v[126:127], v[38:39]
	v_pk_mul_f32 v[132:133], v[132:133], s[68:69]
	v_pk_mul_f32 v[120:121], v[120:121], s[68:69]
	v_pk_mul_f32 v[134:135], v[134:135], s[68:69]
	v_pk_mul_f32 v[122:123], v[122:123], s[68:69]
	v_pk_mul_f32 v[128:129], v[128:129], s[68:69]
	v_pk_mul_f32 v[124:125], v[124:125], s[68:69]
	v_pk_mul_f32 v[130:131], v[130:131], s[68:69]
	v_pk_mul_f32 v[126:127], v[126:127], s[68:69]
	v_exp_f32_e32 v132, v132
	v_exp_f32_e32 v133, v133
	v_exp_f32_e32 v134, v134
	v_exp_f32_e32 v135, v135
	v_exp_f32_e32 v128, v128
	v_exp_f32_e32 v129, v129
	v_exp_f32_e32 v130, v130
	v_exp_f32_e32 v131, v131
	v_exp_f32_e32 v120, v120
	v_exp_f32_e32 v121, v121
	v_exp_f32_e32 v122, v122
	v_exp_f32_e32 v123, v123
	v_exp_f32_e32 v124, v124
	v_exp_f32_e32 v125, v125
	v_exp_f32_e32 v126, v126
	v_exp_f32_e32 v127, v127
	v_pk_add_f32 v[132:133], v[132:133], s[72:73]
	v_pk_add_f32 v[120:121], v[120:121], s[72:73]
	v_pk_add_f32 v[134:135], v[134:135], s[72:73]
	v_pk_add_f32 v[122:123], v[122:123], s[72:73]
	v_pk_add_f32 v[128:129], v[128:129], s[72:73]
	v_pk_add_f32 v[124:125], v[124:125], s[72:73]
	v_pk_add_f32 v[130:131], v[130:131], s[72:73]
	v_pk_add_f32 v[126:127], v[126:127], s[72:73]
	v_rcp_f32_e32 v132, v132
	v_rcp_f32_e32 v133, v133
	v_rcp_f32_e32 v134, v134
	v_rcp_f32_e32 v135, v135
	v_rcp_f32_e32 v128, v128
	v_rcp_f32_e32 v129, v129
	v_rcp_f32_e32 v130, v130
	v_rcp_f32_e32 v131, v131
	v_rcp_f32_e32 v120, v120
	v_rcp_f32_e32 v121, v121
	v_rcp_f32_e32 v122, v122
	v_rcp_f32_e32 v123, v123
	v_rcp_f32_e32 v124, v124
	v_rcp_f32_e32 v125, v125
	v_rcp_f32_e32 v126, v126
	v_rcp_f32_e32 v127, v127
	v_lshlrev_b32_e32 v230, 16, v156
	v_and_b32_e32 v231, 0xffff0000, v156
	v_lshlrev_b32_e32 v234, 16, v157
	v_and_b32_e32 v235, 0xffff0000, v157
	v_lshlrev_b32_e32 v236, 16, v158
	v_and_b32_e32 v237, 0xffff0000, v158
	v_lshlrev_b32_e32 v238, 16, v159
	v_and_b32_e32 v239, 0xffff0000, v159
	v_pk_mul_f32 v[132:133], v[64:65], v[132:133]
	v_pk_mul_f32 v[134:135], v[66:67], v[134:135]
	v_pk_mul_f32 v[128:129], v[52:53], v[128:129]
	v_pk_mul_f32 v[130:131], v[54:55], v[130:131]
	v_pk_mul_f32 v[120:121], v[120:121], v[230:231]
	v_pk_mul_f32 v[122:123], v[122:123], v[234:235]
	v_pk_mul_f32 v[124:125], v[124:125], v[236:237]
	v_pk_mul_f32 v[126:127], v[126:127], v[238:239]
	v_pk_add_f32 v[198:199], v[132:133], v[132:133]
	v_pk_add_f32 v[200:201], v[134:135], v[134:135]
	v_pk_mul_f32 v[206:207], v[198:199], s[70:71]
	v_pk_mul_f32 v[208:209], v[200:201], s[70:71]
	v_pk_fma_f32 v[202:203], v[198:199], s[74:75], v[222:223]
	v_pk_fma_f32 v[204:205], v[200:201], s[74:75], v[222:223]
	v_exp_f32_e32 v206, v206
	v_exp_f32_e32 v207, v207
	v_exp_f32_e32 v208, v208
	v_exp_f32_e32 v209, v209
	v_pk_fma_f32 v[202:203], v[198:199], v[202:203], s[76:77]
	v_pk_fma_f32 v[204:205], v[200:201], v[204:205], s[76:77]
	v_pk_fma_f32 v[202:203], v[198:199], v[202:203], s[72:73]
	v_pk_fma_f32 v[204:205], v[200:201], v[204:205], s[72:73]
	v_pk_mul_f32 v[202:203], v[202:203], v[198:199] neg_lo:[0,1] neg_hi:[0,1]
	v_pk_mul_f32 v[204:205], v[204:205], v[200:201] neg_lo:[0,1] neg_hi:[0,1]
	v_pk_add_f32 v[206:207], s[72:73], v[206:207] neg_lo:[0,1] neg_hi:[0,1]
	v_pk_add_f32 v[208:209], s[72:73], v[208:209] neg_lo:[0,1] neg_hi:[0,1]
	v_cmp_lt_f32_e64 s[78:79], s4, v198
	v_cmp_lt_f32_e64 s[80:81], s4, v199
	v_cmp_lt_f32_e64 s[82:83], s4, v200
	v_cmp_lt_f32_e64 s[24:25], s4, v201
	v_cndmask_b32_e64 v202, v206, v202, s[78:79]
	v_cndmask_b32_e64 v203, v207, v203, s[80:81]
	v_cndmask_b32_e64 v204, v208, v204, s[82:83]
	v_cndmask_b32_e64 v205, v209, v205, s[24:25]
	v_sqrt_f32_e32 v202, v202
	v_sqrt_f32_e32 v203, v203
	v_sqrt_f32_e32 v204, v204
	v_sqrt_f32_e32 v205, v205
	v_pk_mul_f32 v[120:121], v[120:121], v[202:203]
	v_pk_mul_f32 v[122:123], v[122:123], v[204:205]
	v_pk_add_f32 v[198:199], v[128:129], v[128:129]
	v_pk_add_f32 v[200:201], v[130:131], v[130:131]
; __device__ __forceinline__ unsigned pk2(float lo, float hi) { unsigned r; asm("v_cvt_pk_bf16_f32 %0, %1, %2" : "=v"(r) : "v"(lo), "v"(hi)); return r; }
; __device__ __forceinline__ float sigmoidf_(float x) { return __builtin_amdgcn_rcpf(1.0f + __expf(-x)); }
;     __device__ __forceinline__ void operator()(const f32x4 (&acc)[2][2][4][2], const Unit& u, int wr, int wc, int fr, int fq) const {
;     ...
;         for (int ai = 0; ai < 2; ++ai)
; #pragma unroll
;             for (int m = 0; m < 4; ++m) { const size_t off = (size_t)(row0 + ai * HALF + m * 16) * LW + ch0;
;                 float xc[8]; unpack8(xraw[ai][m], xc);
;                 float la[8], uu[8];
; #pragma unroll
;                 for (int n = 0; n < 2; ++n)
; #pragma unroll
;                     for (int j = 0; j < 4; ++j) { const int e = 4 * n + j;
;                         const float r = sigmoidf_(acc[ai][0][m][n][j] + br[e]), ig = sigmoidf_(acc[ai][1][m][n][j] + bi[e]);
;                         const float l = -8.0f * r * sp[e]; la[e] = l;
;                         const float x2 = 2.0f * l;
;                         const float om = x2 > -0.03125f ? -x2 * (1.0f + x2 * (0.5f + x2 * (0.16666667f + x2 * 0.041666668f))) : 1.0f - __expf(x2);
;                         uu[e] = __builtin_amdgcn_sqrtf(om) * (ig * xc[e]); }
;                 u32x4 w0, w1; w0.x = pk2(la[0], uu[0]); w0.y = pk2(la[1], uu[1]); w0.z = pk2(la[2], uu[2]); w0.w = pk2(la[3], uu[3]);
;                 w1.x = pk2(la[4], uu[4]); w1.y = pk2(la[5], uu[5]); w1.z = pk2(la[6], uu[6]); w1.w = pk2(la[7], uu[7]);
;                 *(u32x4*)(LU + off) = w0; *(u32x4*)(LU + off + 4) = w1; }
	v_pk_mul_f32 v[206:207], v[198:199], s[70:71]
	v_pk_mul_f32 v[208:209], v[200:201], s[70:71]
	v_pk_fma_f32 v[202:203], v[198:199], s[74:75], v[222:223]
	v_pk_fma_f32 v[204:205], v[200:201], s[74:75], v[222:223]
	v_exp_f32_e32 v206, v206
	v_exp_f32_e32 v207, v207
	v_exp_f32_e32 v208, v208
	v_exp_f32_e32 v209, v209
	v_pk_fma_f32 v[202:203], v[198:199], v[202:203], s[76:77]
	v_pk_fma_f32 v[204:205], v[200:201], v[204:205], s[76:77]
	v_pk_fma_f32 v[202:203], v[198:199], v[202:203], s[72:73]
	v_pk_fma_f32 v[204:205], v[200:201], v[204:205], s[72:73]
	v_pk_mul_f32 v[202:203], v[202:203], v[198:199] neg_lo:[0,1] neg_hi:[0,1]
	v_pk_mul_f32 v[204:205], v[204:205], v[200:201] neg_lo:[0,1] neg_hi:[0,1]
	v_pk_add_f32 v[206:207], s[72:73], v[206:207] neg_lo:[0,1] neg_hi:[0,1]
	v_pk_add_f32 v[208:209], s[72:73], v[208:209] neg_lo:[0,1] neg_hi:[0,1]
	v_cmp_lt_f32_e64 s[78:79], s4, v198
	v_cmp_lt_f32_e64 s[80:81], s4, v199
	v_cmp_lt_f32_e64 s[82:83], s4, v200
	v_cmp_lt_f32_e64 s[24:25], s4, v201
	v_cndmask_b32_e64 v202, v206, v202, s[78:79]
	v_cndmask_b32_e64 v203, v207, v203, s[80:81]
	v_cndmask_b32_e64 v204, v208, v204, s[82:83]
	v_cndmask_b32_e64 v205, v209, v205, s[24:25]
	v_sqrt_f32_e32 v202, v202
	v_sqrt_f32_e32 v203, v203
	v_sqrt_f32_e32 v204, v204
	v_sqrt_f32_e32 v205, v205
	v_pk_mul_f32 v[124:125], v[124:125], v[202:203]
	v_pk_mul_f32 v[126:127], v[126:127], v[204:205]
	v_cvt_pk_bf16_f32 v120, v132, v120
	v_cvt_pk_bf16_f32 v121, v133, v121
	v_cvt_pk_bf16_f32 v122, v134, v122
	v_cvt_pk_bf16_f32 v123, v135, v123
	v_cvt_pk_bf16_f32 v124, v128, v124
	v_cvt_pk_bf16_f32 v125, v129, v125
	v_cvt_pk_bf16_f32 v126, v130, v126
	v_cvt_pk_bf16_f32 v127, v131, v127
	v_add_u32_e32 v197, 0x40000, v225
	global_store_dwordx4 v197, v[120:123], s[44:45]
	global_store_dwordx4 v197, v[124:127], s[44:45] offset:16
	v_pk_add_f32 v[112:113], v[112:113], v[68:69]
	v_pk_add_f32 v[100:101], v[100:101], v[32:33]
	v_pk_add_f32 v[114:115], v[114:115], v[70:71]
	v_pk_add_f32 v[102:103], v[102:103], v[34:35]
	v_pk_add_f32 v[108:109], v[108:109], v[56:57]
	v_pk_add_f32 v[104:105], v[104:105], v[36:37]
	v_pk_add_f32 v[110:111], v[110:111], v[58:59]
	v_pk_add_f32 v[106:107], v[106:107], v[38:39]
	v_pk_mul_f32 v[112:113], v[112:113], s[68:69]
	v_pk_mul_f32 v[100:101], v[100:101], s[68:69]
	v_pk_mul_f32 v[114:115], v[114:115], s[68:69]
	v_pk_mul_f32 v[102:103], v[102:103], s[68:69]
	v_pk_mul_f32 v[108:109], v[108:109], s[68:69]
	v_pk_mul_f32 v[104:105], v[104:105], s[68:69]
	v_pk_mul_f32 v[110:111], v[110:111], s[68:69]
	v_pk_mul_f32 v[106:107], v[106:107], s[68:69]
	v_exp_f32_e32 v112, v112
	v_exp_f32_e32 v113, v113
	v_exp_f32_e32 v114, v114
	v_exp_f32_e32 v115, v115
	v_exp_f32_e32 v108, v108
	v_exp_f32_e32 v109, v109
	v_exp_f32_e32 v110, v110
	v_exp_f32_e32 v111, v111
	v_exp_f32_e32 v100, v100
	v_exp_f32_e32 v101, v101
	v_exp_f32_e32 v102, v102
	v_exp_f32_e32 v103, v103
	v_exp_f32_e32 v104, v104
	v_exp_f32_e32 v105, v105
	v_exp_f32_e32 v106, v106
	v_exp_f32_e32 v107, v107
	v_pk_add_f32 v[112:113], v[112:113], s[72:73]
	v_pk_add_f32 v[100:101], v[100:101], s[72:73]
	v_pk_add_f32 v[114:115], v[114:115], s[72:73]
	v_pk_add_f32 v[102:103], v[102:103], s[72:73]
	v_pk_add_f32 v[108:109], v[108:109], s[72:73]
	v_pk_add_f32 v[104:105], v[104:105], s[72:73]
	v_pk_add_f32 v[110:111], v[110:111], s[72:73]
	v_pk_add_f32 v[106:107], v[106:107], s[72:73]
	v_rcp_f32_e32 v112, v112
	v_rcp_f32_e32 v113, v113
	v_rcp_f32_e32 v114, v114
	v_rcp_f32_e32 v115, v115
	v_rcp_f32_e32 v108, v108
	v_rcp_f32_e32 v109, v109
	v_rcp_f32_e32 v110, v110
	v_rcp_f32_e32 v111, v111
	v_rcp_f32_e32 v100, v100
	v_rcp_f32_e32 v101, v101
	v_rcp_f32_e32 v102, v102
	v_rcp_f32_e32 v103, v103
	v_rcp_f32_e32 v104, v104
	v_rcp_f32_e32 v105, v105
	v_rcp_f32_e32 v106, v106
	v_rcp_f32_e32 v107, v107
	v_lshlrev_b32_e32 v230, 16, v136
	v_and_b32_e32 v231, 0xffff0000, v136
	v_lshlrev_b32_e32 v234, 16, v137
	v_and_b32_e32 v235, 0xffff0000, v137
	v_lshlrev_b32_e32 v236, 16, v138
	v_and_b32_e32 v237, 0xffff0000, v138
	v_lshlrev_b32_e32 v238, 16, v139
	v_and_b32_e32 v239, 0xffff0000, v139
	v_pk_mul_f32 v[112:113], v[64:65], v[112:113]
	v_pk_mul_f32 v[114:115], v[66:67], v[114:115]
	v_pk_mul_f32 v[108:109], v[52:53], v[108:109]
	v_pk_mul_f32 v[110:111], v[54:55], v[110:111]
	v_pk_mul_f32 v[100:101], v[100:101], v[230:231]
	v_pk_mul_f32 v[102:103], v[102:103], v[234:235]
	v_pk_mul_f32 v[104:105], v[104:105], v[236:237]
	v_pk_mul_f32 v[106:107], v[106:107], v[238:239]
	v_pk_add_f32 v[198:199], v[112:113], v[112:113]
	v_pk_add_f32 v[200:201], v[114:115], v[114:115]
	v_pk_mul_f32 v[206:207], v[198:199], s[70:71]
	v_pk_mul_f32 v[208:209], v[200:201], s[70:71]
	v_pk_fma_f32 v[202:203], v[198:199], s[74:75], v[222:223]
	v_pk_fma_f32 v[204:205], v[200:201], s[74:75], v[222:223]
	v_exp_f32_e32 v206, v206
	v_exp_f32_e32 v207, v207
	v_exp_f32_e32 v208, v208
	v_exp_f32_e32 v209, v209
	v_pk_fma_f32 v[202:203], v[198:199], v[202:203], s[76:77]
	v_pk_fma_f32 v[204:205], v[200:201], v[204:205], s[76:77]
	v_pk_fma_f32 v[202:203], v[198:199], v[202:203], s[72:73]
	v_pk_fma_f32 v[204:205], v[200:201], v[204:205], s[72:73]
	v_pk_mul_f32 v[202:203], v[202:203], v[198:199] neg_lo:[0,1] neg_hi:[0,1]
	v_pk_mul_f32 v[204:205], v[204:205], v[200:201] neg_lo:[0,1] neg_hi:[0,1]
	v_pk_add_f32 v[206:207], s[72:73], v[206:207] neg_lo:[0,1] neg_hi:[0,1]
	v_pk_add_f32 v[208:209], s[72:73], v[208:209] neg_lo:[0,1] neg_hi:[0,1]
	v_cmp_lt_f32_e64 s[78:79], s4, v198
	v_cmp_lt_f32_e64 s[80:81], s4, v199
	v_cmp_lt_f32_e64 s[82:83], s4, v200
	v_cmp_lt_f32_e64 s[24:25], s4, v201
	v_cndmask_b32_e64 v202, v206, v202, s[78:79]
	v_cndmask_b32_e64 v203, v207, v203, s[80:81]
; __device__ __forceinline__ unsigned pk2(float lo, float hi) { unsigned r; asm("v_cvt_pk_bf16_f32 %0, %1, %2" : "=v"(r) : "v"(lo), "v"(hi)); return r; }
; __device__ __forceinline__ float sigmoidf_(float x) { return __builtin_amdgcn_rcpf(1.0f + __expf(-x)); }
;     __device__ __forceinline__ void operator()(const f32x4 (&acc)[2][2][4][2], const Unit& u, int wr, int wc, int fr, int fq) const {
;     ...
;         for (int ai = 0; ai < 2; ++ai)
; #pragma unroll
;             for (int m = 0; m < 4; ++m) { const size_t off = (size_t)(row0 + ai * HALF + m * 16) * LW + ch0;
;                 float xc[8]; unpack8(xraw[ai][m], xc);
;                 float la[8], uu[8];
; #pragma unroll
;                 for (int n = 0; n < 2; ++n)
; #pragma unroll
;                     for (int j = 0; j < 4; ++j) { const int e = 4 * n + j;
;                         const float r = sigmoidf_(acc[ai][0][m][n][j] + br[e]), ig = sigmoidf_(acc[ai][1][m][n][j] + bi[e]);
;                         const float l = -8.0f * r * sp[e]; la[e] = l;
;                         const float x2 = 2.0f * l;
;                         const float om = x2 > -0.03125f ? -x2 * (1.0f + x2 * (0.5f + x2 * (0.16666667f + x2 * 0.041666668f))) : 1.0f - __expf(x2);
;                         uu[e] = __builtin_amdgcn_sqrtf(om) * (ig * xc[e]); }
;                 u32x4 w0, w1; w0.x = pk2(la[0], uu[0]); w0.y = pk2(la[1], uu[1]); w0.z = pk2(la[2], uu[2]); w0.w = pk2(la[3], uu[3]);
;                 w1.x = pk2(la[4], uu[4]); w1.y = pk2(la[5], uu[5]); w1.z = pk2(la[6], uu[6]); w1.w = pk2(la[7], uu[7]);
;                 *(u32x4*)(LU + off) = w0; *(u32x4*)(LU + off + 4) = w1; }
	v_cndmask_b32_e64 v204, v208, v204, s[82:83]
	v_cndmask_b32_e64 v205, v209, v205, s[24:25]
	v_sqrt_f32_e32 v202, v202
	v_sqrt_f32_e32 v203, v203
	v_sqrt_f32_e32 v204, v204
	v_sqrt_f32_e32 v205, v205
	v_pk_mul_f32 v[100:101], v[100:101], v[202:203]
	v_pk_mul_f32 v[102:103], v[102:103], v[204:205]
	v_pk_add_f32 v[198:199], v[108:109], v[108:109]
	v_pk_add_f32 v[200:201], v[110:111], v[110:111]
	v_pk_mul_f32 v[206:207], v[198:199], s[70:71]
	v_pk_mul_f32 v[208:209], v[200:201], s[70:71]
	v_pk_fma_f32 v[202:203], v[198:199], s[74:75], v[222:223]
	v_pk_fma_f32 v[204:205], v[200:201], s[74:75], v[222:223]
	v_exp_f32_e32 v206, v206
	v_exp_f32_e32 v207, v207
	v_exp_f32_e32 v208, v208
	v_exp_f32_e32 v209, v209
	v_pk_fma_f32 v[202:203], v[198:199], v[202:203], s[76:77]
	v_pk_fma_f32 v[204:205], v[200:201], v[204:205], s[76:77]
	v_pk_fma_f32 v[202:203], v[198:199], v[202:203], s[72:73]
	v_pk_fma_f32 v[204:205], v[200:201], v[204:205], s[72:73]
	v_pk_mul_f32 v[202:203], v[202:203], v[198:199] neg_lo:[0,1] neg_hi:[0,1]
	v_pk_mul_f32 v[204:205], v[204:205], v[200:201] neg_lo:[0,1] neg_hi:[0,1]
	v_pk_add_f32 v[206:207], s[72:73], v[206:207] neg_lo:[0,1] neg_hi:[0,1]
	v_pk_add_f32 v[208:209], s[72:73], v[208:209] neg_lo:[0,1] neg_hi:[0,1]
	v_cmp_lt_f32_e64 s[78:79], s4, v198
	v_cmp_lt_f32_e64 s[80:81], s4, v199
	v_cmp_lt_f32_e64 s[82:83], s4, v200
	v_cmp_lt_f32_e64 s[24:25], s4, v201
	v_cndmask_b32_e64 v202, v206, v202, s[78:79]
	v_cndmask_b32_e64 v203, v207, v203, s[80:81]
	v_cndmask_b32_e64 v204, v208, v204, s[82:83]
	v_cndmask_b32_e64 v205, v209, v205, s[24:25]
	v_sqrt_f32_e32 v202, v202
	v_sqrt_f32_e32 v203, v203
	v_sqrt_f32_e32 v204, v204
	v_sqrt_f32_e32 v205, v205
	v_pk_mul_f32 v[104:105], v[104:105], v[202:203]
	v_pk_mul_f32 v[106:107], v[106:107], v[204:205]
	v_cvt_pk_bf16_f32 v100, v112, v100
	v_cvt_pk_bf16_f32 v101, v113, v101
	v_cvt_pk_bf16_f32 v102, v114, v102
	v_cvt_pk_bf16_f32 v103, v115, v103
	v_cvt_pk_bf16_f32 v104, v108, v104
	v_cvt_pk_bf16_f32 v105, v109, v105
	v_cvt_pk_bf16_f32 v106, v110, v106
	v_cvt_pk_bf16_f32 v107, v111, v107
	v_add_u32_e32 v197, 0x60000, v225
	global_store_dwordx4 v197, v[100:103], s[44:45]
	global_store_dwordx4 v197, v[104:107], s[44:45] offset:16
	v_pk_add_f32 v[92:93], v[92:93], v[68:69]
	v_pk_add_f32 v[80:81], v[80:81], v[32:33]
	v_pk_add_f32 v[94:95], v[94:95], v[70:71]
	v_pk_add_f32 v[82:83], v[82:83], v[34:35]
	v_pk_add_f32 v[88:89], v[88:89], v[56:57]
	v_pk_add_f32 v[84:85], v[84:85], v[36:37]
	v_pk_add_f32 v[90:91], v[90:91], v[58:59]
	v_pk_add_f32 v[86:87], v[86:87], v[38:39]
	v_pk_mul_f32 v[92:93], v[92:93], s[68:69]
	v_pk_mul_f32 v[80:81], v[80:81], s[68:69]
	v_pk_mul_f32 v[94:95], v[94:95], s[68:69]
	v_pk_mul_f32 v[82:83], v[82:83], s[68:69]
	v_pk_mul_f32 v[88:89], v[88:89], s[68:69]
	v_pk_mul_f32 v[84:85], v[84:85], s[68:69]
	v_pk_mul_f32 v[90:91], v[90:91], s[68:69]
	v_pk_mul_f32 v[86:87], v[86:87], s[68:69]
	v_exp_f32_e32 v92, v92
	v_exp_f32_e32 v93, v93
	v_exp_f32_e32 v94, v94
	v_exp_f32_e32 v95, v95
	v_exp_f32_e32 v88, v88
	v_exp_f32_e32 v89, v89
	v_exp_f32_e32 v90, v90
	v_exp_f32_e32 v91, v91
	v_exp_f32_e32 v80, v80
	v_exp_f32_e32 v81, v81
	v_exp_f32_e32 v82, v82
	v_exp_f32_e32 v83, v83
	v_exp_f32_e32 v84, v84
	v_exp_f32_e32 v85, v85
	v_exp_f32_e32 v86, v86
	v_exp_f32_e32 v87, v87
	v_pk_add_f32 v[92:93], v[92:93], s[72:73]
	v_pk_add_f32 v[80:81], v[80:81], s[72:73]
	v_pk_add_f32 v[94:95], v[94:95], s[72:73]
	v_pk_add_f32 v[82:83], v[82:83], s[72:73]
	v_pk_add_f32 v[88:89], v[88:89], s[72:73]
	v_pk_add_f32 v[84:85], v[84:85], s[72:73]
	v_pk_add_f32 v[90:91], v[90:91], s[72:73]
	v_pk_add_f32 v[86:87], v[86:87], s[72:73]
	v_rcp_f32_e32 v92, v92
	v_rcp_f32_e32 v93, v93
	v_rcp_f32_e32 v94, v94
	v_rcp_f32_e32 v95, v95
	v_rcp_f32_e32 v88, v88
	v_rcp_f32_e32 v89, v89
	v_rcp_f32_e32 v90, v90
	v_rcp_f32_e32 v91, v91
	v_rcp_f32_e32 v80, v80
	v_rcp_f32_e32 v81, v81
	v_rcp_f32_e32 v82, v82
	v_rcp_f32_e32 v83, v83
	v_rcp_f32_e32 v84, v84
	v_rcp_f32_e32 v85, v85
	v_rcp_f32_e32 v86, v86
	v_rcp_f32_e32 v87, v87
	v_lshlrev_b32_e32 v230, 16, v116
	v_and_b32_e32 v231, 0xffff0000, v116
	v_lshlrev_b32_e32 v234, 16, v117
	v_and_b32_e32 v235, 0xffff0000, v117
	v_lshlrev_b32_e32 v236, 16, v118
	v_and_b32_e32 v237, 0xffff0000, v118
	v_lshlrev_b32_e32 v238, 16, v119
	v_and_b32_e32 v239, 0xffff0000, v119
	v_pk_mul_f32 v[92:93], v[64:65], v[92:93]
	v_pk_mul_f32 v[94:95], v[66:67], v[94:95]
	v_pk_mul_f32 v[88:89], v[52:53], v[88:89]
	v_pk_mul_f32 v[90:91], v[54:55], v[90:91]
	v_pk_mul_f32 v[80:81], v[80:81], v[230:231]
	v_pk_mul_f32 v[82:83], v[82:83], v[234:235]
	v_pk_mul_f32 v[84:85], v[84:85], v[236:237]
	v_pk_mul_f32 v[86:87], v[86:87], v[238:239]
	v_pk_add_f32 v[198:199], v[92:93], v[92:93]
	v_pk_add_f32 v[200:201], v[94:95], v[94:95]
	v_pk_mul_f32 v[206:207], v[198:199], s[70:71]
	v_pk_mul_f32 v[208:209], v[200:201], s[70:71]
	v_pk_fma_f32 v[202:203], v[198:199], s[74:75], v[222:223]
	v_pk_fma_f32 v[204:205], v[200:201], s[74:75], v[222:223]
	v_exp_f32_e32 v206, v206
	v_exp_f32_e32 v207, v207
	v_exp_f32_e32 v208, v208
	v_exp_f32_e32 v209, v209
	v_pk_fma_f32 v[202:203], v[198:199], v[202:203], s[76:77]
	v_pk_fma_f32 v[204:205], v[200:201], v[204:205], s[76:77]
	v_pk_fma_f32 v[202:203], v[198:199], v[202:203], s[72:73]
	v_pk_fma_f32 v[204:205], v[200:201], v[204:205], s[72:73]
	v_pk_mul_f32 v[202:203], v[202:203], v[198:199] neg_lo:[0,1] neg_hi:[0,1]
	v_pk_mul_f32 v[204:205], v[204:205], v[200:201] neg_lo:[0,1] neg_hi:[0,1]
	v_pk_add_f32 v[206:207], s[72:73], v[206:207] neg_lo:[0,1] neg_hi:[0,1]
	v_pk_add_f32 v[208:209], s[72:73], v[208:209] neg_lo:[0,1] neg_hi:[0,1]
	v_cmp_lt_f32_e64 s[78:79], s4, v198
; __device__ __forceinline__ unsigned pk2(float lo, float hi) { unsigned r; asm("v_cvt_pk_bf16_f32 %0, %1, %2" : "=v"(r) : "v"(lo), "v"(hi)); return r; }
; __device__ __forceinline__ float sigmoidf_(float x) { return __builtin_amdgcn_rcpf(1.0f + __expf(-x)); }
;     __device__ __forceinline__ void operator()(const f32x4 (&acc)[2][2][4][2], const Unit& u, int wr, int wc, int fr, int fq) const {
;     ...
;         for (int ai = 0; ai < 2; ++ai)
; #pragma unroll
;             for (int m = 0; m < 4; ++m) { const size_t off = (size_t)(row0 + ai * HALF + m * 16) * LW + ch0;
;                 float xc[8]; unpack8(xraw[ai][m], xc);
;                 float la[8], uu[8];
; #pragma unroll
;                 for (int n = 0; n < 2; ++n)
; #pragma unroll
;                     for (int j = 0; j < 4; ++j) { const int e = 4 * n + j;
;                         const float r = sigmoidf_(acc[ai][0][m][n][j] + br[e]), ig = sigmoidf_(acc[ai][1][m][n][j] + bi[e]);
;                         const float l = -8.0f * r * sp[e]; la[e] = l;
;                         const float x2 = 2.0f * l;
;                         const float om = x2 > -0.03125f ? -x2 * (1.0f + x2 * (0.5f + x2 * (0.16666667f + x2 * 0.041666668f))) : 1.0f - __expf(x2);
;                         uu[e] = __builtin_amdgcn_sqrtf(om) * (ig * xc[e]); }
;                 u32x4 w0, w1; w0.x = pk2(la[0], uu[0]); w0.y = pk2(la[1], uu[1]); w0.z = pk2(la[2], uu[2]); w0.w = pk2(la[3], uu[3]);
;                 w1.x = pk2(la[4], uu[4]); w1.y = pk2(la[5], uu[5]); w1.z = pk2(la[6], uu[6]); w1.w = pk2(la[7], uu[7]);
;                 *(u32x4*)(LU + off) = w0; *(u32x4*)(LU + off + 4) = w1; }
	v_cmp_lt_f32_e64 s[80:81], s4, v199
	v_cmp_lt_f32_e64 s[82:83], s4, v200
	v_cmp_lt_f32_e64 s[24:25], s4, v201
	v_cndmask_b32_e64 v202, v206, v202, s[78:79]
	v_cndmask_b32_e64 v203, v207, v203, s[80:81]
	v_cndmask_b32_e64 v204, v208, v204, s[82:83]
	v_cndmask_b32_e64 v205, v209, v205, s[24:25]
	v_sqrt_f32_e32 v202, v202
	v_sqrt_f32_e32 v203, v203
	v_sqrt_f32_e32 v204, v204
	v_sqrt_f32_e32 v205, v205
	v_pk_mul_f32 v[80:81], v[80:81], v[202:203]
	v_pk_mul_f32 v[82:83], v[82:83], v[204:205]
	v_pk_add_f32 v[198:199], v[88:89], v[88:89]
	v_pk_add_f32 v[200:201], v[90:91], v[90:91]
	v_pk_mul_f32 v[206:207], v[198:199], s[70:71]
	v_pk_mul_f32 v[208:209], v[200:201], s[70:71]
	v_pk_fma_f32 v[202:203], v[198:199], s[74:75], v[222:223]
	v_pk_fma_f32 v[204:205], v[200:201], s[74:75], v[222:223]
	v_exp_f32_e32 v206, v206
	v_exp_f32_e32 v207, v207
	v_exp_f32_e32 v208, v208
	v_exp_f32_e32 v209, v209
	v_pk_fma_f32 v[202:203], v[198:199], v[202:203], s[76:77]
	v_pk_fma_f32 v[204:205], v[200:201], v[204:205], s[76:77]
	v_pk_fma_f32 v[202:203], v[198:199], v[202:203], s[72:73]
	v_pk_fma_f32 v[204:205], v[200:201], v[204:205], s[72:73]
	v_pk_mul_f32 v[202:203], v[202:203], v[198:199] neg_lo:[0,1] neg_hi:[0,1]
	v_pk_mul_f32 v[204:205], v[204:205], v[200:201] neg_lo:[0,1] neg_hi:[0,1]
	v_pk_add_f32 v[206:207], s[72:73], v[206:207] neg_lo:[0,1] neg_hi:[0,1]
	v_pk_add_f32 v[208:209], s[72:73], v[208:209] neg_lo:[0,1] neg_hi:[0,1]
	v_cmp_lt_f32_e64 s[78:79], s4, v198
	v_cmp_lt_f32_e64 s[80:81], s4, v199
	v_cmp_lt_f32_e64 s[82:83], s4, v200
	v_cmp_lt_f32_e64 s[24:25], s4, v201
	v_cndmask_b32_e64 v202, v206, v202, s[78:79]
	v_cndmask_b32_e64 v203, v207, v203, s[80:81]
	v_cndmask_b32_e64 v204, v208, v204, s[82:83]
	v_cndmask_b32_e64 v205, v209, v205, s[24:25]
	v_sqrt_f32_e32 v202, v202
	v_sqrt_f32_e32 v203, v203
	v_sqrt_f32_e32 v204, v204
	v_sqrt_f32_e32 v205, v205
	v_pk_mul_f32 v[84:85], v[84:85], v[202:203]
	v_pk_mul_f32 v[86:87], v[86:87], v[204:205]
	v_cvt_pk_bf16_f32 v80, v92, v80
	v_cvt_pk_bf16_f32 v81, v93, v81
	v_cvt_pk_bf16_f32 v82, v94, v82
	v_cvt_pk_bf16_f32 v83, v95, v83
	v_cvt_pk_bf16_f32 v84, v88, v84
	v_cvt_pk_bf16_f32 v85, v89, v85
	v_cvt_pk_bf16_f32 v86, v90, v86
	v_cvt_pk_bf16_f32 v87, v91, v87
	v_add_u32_e32 v197, 0x100000, v225
	global_store_dwordx4 v197, v[80:83], s[44:45]
	global_store_dwordx4 v197, v[84:87], s[44:45] offset:16
	v_pk_add_f32 v[72:73], v[72:73], v[68:69]
	v_pk_add_f32 v[40:41], v[40:41], v[32:33]
	v_pk_add_f32 v[74:75], v[74:75], v[70:71]
	v_pk_add_f32 v[42:43], v[42:43], v[34:35]
	v_pk_add_f32 v[60:61], v[60:61], v[56:57]
	v_pk_add_f32 v[44:45], v[44:45], v[36:37]
	v_pk_add_f32 v[62:63], v[62:63], v[58:59]
	v_pk_add_f32 v[46:47], v[46:47], v[38:39]
	v_pk_mul_f32 v[72:73], v[72:73], s[68:69]
	v_pk_mul_f32 v[40:41], v[40:41], s[68:69]
	v_pk_mul_f32 v[74:75], v[74:75], s[68:69]
	v_pk_mul_f32 v[42:43], v[42:43], s[68:69]
	v_pk_mul_f32 v[60:61], v[60:61], s[68:69]
	v_pk_mul_f32 v[44:45], v[44:45], s[68:69]
	v_pk_mul_f32 v[62:63], v[62:63], s[68:69]
	v_pk_mul_f32 v[46:47], v[46:47], s[68:69]
	v_exp_f32_e32 v72, v72
	v_exp_f32_e32 v73, v73
	v_exp_f32_e32 v74, v74
	v_exp_f32_e32 v75, v75
	v_exp_f32_e32 v60, v60
	v_exp_f32_e32 v61, v61
	v_exp_f32_e32 v62, v62
	v_exp_f32_e32 v63, v63
	v_exp_f32_e32 v40, v40
	v_exp_f32_e32 v41, v41
	v_exp_f32_e32 v42, v42
	v_exp_f32_e32 v43, v43
	v_exp_f32_e32 v44, v44
	v_exp_f32_e32 v45, v45
	v_exp_f32_e32 v46, v46
	v_exp_f32_e32 v47, v47
	v_pk_add_f32 v[72:73], v[72:73], s[72:73]
	v_pk_add_f32 v[40:41], v[40:41], s[72:73]
	v_pk_add_f32 v[74:75], v[74:75], s[72:73]
	v_pk_add_f32 v[42:43], v[42:43], s[72:73]
	v_pk_add_f32 v[60:61], v[60:61], s[72:73]
	v_pk_add_f32 v[44:45], v[44:45], s[72:73]
	v_pk_add_f32 v[62:63], v[62:63], s[72:73]
	v_pk_add_f32 v[46:47], v[46:47], s[72:73]
	v_rcp_f32_e32 v72, v72
	v_rcp_f32_e32 v73, v73
	v_rcp_f32_e32 v74, v74
	v_rcp_f32_e32 v75, v75
	v_rcp_f32_e32 v60, v60
	v_rcp_f32_e32 v61, v61
	v_rcp_f32_e32 v62, v62
	v_rcp_f32_e32 v63, v63
	v_rcp_f32_e32 v40, v40
	v_rcp_f32_e32 v41, v41
	v_rcp_f32_e32 v42, v42
	v_rcp_f32_e32 v43, v43
	v_rcp_f32_e32 v44, v44
	v_rcp_f32_e32 v45, v45
	v_rcp_f32_e32 v46, v46
	v_rcp_f32_e32 v47, v47
	v_lshlrev_b32_e32 v230, 16, v96
	v_and_b32_e32 v231, 0xffff0000, v96
	v_lshlrev_b32_e32 v234, 16, v97
	v_and_b32_e32 v235, 0xffff0000, v97
	v_lshlrev_b32_e32 v236, 16, v98
	v_and_b32_e32 v237, 0xffff0000, v98
	v_lshlrev_b32_e32 v238, 16, v99
	v_and_b32_e32 v239, 0xffff0000, v99
	v_pk_mul_f32 v[72:73], v[64:65], v[72:73]
	v_pk_mul_f32 v[74:75], v[66:67], v[74:75]
	v_pk_mul_f32 v[60:61], v[52:53], v[60:61]
	v_pk_mul_f32 v[62:63], v[54:55], v[62:63]
	v_pk_mul_f32 v[40:41], v[40:41], v[230:231]
	v_pk_mul_f32 v[42:43], v[42:43], v[234:235]
	v_pk_mul_f32 v[44:45], v[44:45], v[236:237]
	v_pk_mul_f32 v[46:47], v[46:47], v[238:239]
	v_pk_add_f32 v[198:199], v[72:73], v[72:73]
	v_pk_add_f32 v[200:201], v[74:75], v[74:75]
	v_pk_mul_f32 v[206:207], v[198:199], s[70:71]
	v_pk_mul_f32 v[208:209], v[200:201], s[70:71]
	v_pk_fma_f32 v[202:203], v[198:199], s[74:75], v[222:223]
	v_pk_fma_f32 v[204:205], v[200:201], s[74:75], v[222:223]
	v_exp_f32_e32 v206, v206
	v_exp_f32_e32 v207, v207
	v_exp_f32_e32 v208, v208
	v_exp_f32_e32 v209, v209
	v_pk_fma_f32 v[202:203], v[198:199], v[202:203], s[76:77]
	v_pk_fma_f32 v[204:205], v[200:201], v[204:205], s[76:77]
	v_pk_fma_f32 v[202:203], v[198:199], v[202:203], s[72:73]
	v_pk_fma_f32 v[204:205], v[200:201], v[204:205], s[72:73]
	v_pk_mul_f32 v[202:203], v[202:203], v[198:199] neg_lo:[0,1] neg_hi:[0,1]
	v_pk_mul_f32 v[204:205], v[204:205], v[200:201] neg_lo:[0,1] neg_hi:[0,1]
	v_pk_add_f32 v[206:207], s[72:73], v[206:207] neg_lo:[0,1] neg_hi:[0,1]
; __device__ __forceinline__ unsigned pk2(float lo, float hi) { unsigned r; asm("v_cvt_pk_bf16_f32 %0, %1, %2" : "=v"(r) : "v"(lo), "v"(hi)); return r; }
; __device__ __forceinline__ float sigmoidf_(float x) { return __builtin_amdgcn_rcpf(1.0f + __expf(-x)); }
;     __device__ __forceinline__ void operator()(const f32x4 (&acc)[2][2][4][2], const Unit& u, int wr, int wc, int fr, int fq) const {
;     ...
;         for (int ai = 0; ai < 2; ++ai)
; #pragma unroll
;             for (int m = 0; m < 4; ++m) { const size_t off = (size_t)(row0 + ai * HALF + m * 16) * LW + ch0;
;                 float xc[8]; unpack8(xraw[ai][m], xc);
;                 float la[8], uu[8];
; #pragma unroll
;                 for (int n = 0; n < 2; ++n)
; #pragma unroll
;                     for (int j = 0; j < 4; ++j) { const int e = 4 * n + j;
;                         const float r = sigmoidf_(acc[ai][0][m][n][j] + br[e]), ig = sigmoidf_(acc[ai][1][m][n][j] + bi[e]);
;                         const float l = -8.0f * r * sp[e]; la[e] = l;
;                         const float x2 = 2.0f * l;
;                         const float om = x2 > -0.03125f ? -x2 * (1.0f + x2 * (0.5f + x2 * (0.16666667f + x2 * 0.041666668f))) : 1.0f - __expf(x2);
;                         uu[e] = __builtin_amdgcn_sqrtf(om) * (ig * xc[e]); }
;                 u32x4 w0, w1; w0.x = pk2(la[0], uu[0]); w0.y = pk2(la[1], uu[1]); w0.z = pk2(la[2], uu[2]); w0.w = pk2(la[3], uu[3]);
;                 w1.x = pk2(la[4], uu[4]); w1.y = pk2(la[5], uu[5]); w1.z = pk2(la[6], uu[6]); w1.w = pk2(la[7], uu[7]);
;                 *(u32x4*)(LU + off) = w0; *(u32x4*)(LU + off + 4) = w1; }
	v_pk_add_f32 v[208:209], s[72:73], v[208:209] neg_lo:[0,1] neg_hi:[0,1]
	v_cmp_lt_f32_e64 s[78:79], s4, v198
	v_cmp_lt_f32_e64 s[80:81], s4, v199
	v_cmp_lt_f32_e64 s[82:83], s4, v200
	v_cmp_lt_f32_e64 s[24:25], s4, v201
	v_cndmask_b32_e64 v202, v206, v202, s[78:79]
	v_cndmask_b32_e64 v203, v207, v203, s[80:81]
	v_cndmask_b32_e64 v204, v208, v204, s[82:83]
	v_cndmask_b32_e64 v205, v209, v205, s[24:25]
	v_sqrt_f32_e32 v202, v202
	v_sqrt_f32_e32 v203, v203
	v_sqrt_f32_e32 v204, v204
	v_sqrt_f32_e32 v205, v205
	v_pk_mul_f32 v[40:41], v[40:41], v[202:203]
	v_pk_mul_f32 v[42:43], v[42:43], v[204:205]
	v_pk_add_f32 v[198:199], v[60:61], v[60:61]
	v_pk_add_f32 v[200:201], v[62:63], v[62:63]
	v_pk_mul_f32 v[206:207], v[198:199], s[70:71]
	v_pk_mul_f32 v[208:209], v[200:201], s[70:71]
	v_pk_fma_f32 v[202:203], v[198:199], s[74:75], v[222:223]
	v_pk_fma_f32 v[204:205], v[200:201], s[74:75], v[222:223]
	v_exp_f32_e32 v206, v206
	v_exp_f32_e32 v207, v207
	v_exp_f32_e32 v208, v208
	v_exp_f32_e32 v209, v209
	v_pk_fma_f32 v[202:203], v[198:199], v[202:203], s[76:77]
	v_pk_fma_f32 v[204:205], v[200:201], v[204:205], s[76:77]
	v_pk_fma_f32 v[202:203], v[198:199], v[202:203], s[72:73]
	v_pk_fma_f32 v[204:205], v[200:201], v[204:205], s[72:73]
	v_pk_mul_f32 v[202:203], v[202:203], v[198:199] neg_lo:[0,1] neg_hi:[0,1]
	v_pk_mul_f32 v[204:205], v[204:205], v[200:201] neg_lo:[0,1] neg_hi:[0,1]
	v_pk_add_f32 v[206:207], s[72:73], v[206:207] neg_lo:[0,1] neg_hi:[0,1]
	v_pk_add_f32 v[208:209], s[72:73], v[208:209] neg_lo:[0,1] neg_hi:[0,1]
	v_cmp_lt_f32_e64 s[78:79], s4, v198
	v_cmp_lt_f32_e64 s[80:81], s4, v199
	v_cmp_lt_f32_e64 s[82:83], s4, v200
	v_cmp_lt_f32_e64 s[24:25], s4, v201
	v_cndmask_b32_e64 v202, v206, v202, s[78:79]
	v_cndmask_b32_e64 v203, v207, v203, s[80:81]
	v_cndmask_b32_e64 v204, v208, v204, s[82:83]
	v_cndmask_b32_e64 v205, v209, v205, s[24:25]
	v_sqrt_f32_e32 v202, v202
	v_sqrt_f32_e32 v203, v203
	v_sqrt_f32_e32 v204, v204
	v_sqrt_f32_e32 v205, v205
	v_pk_mul_f32 v[44:45], v[44:45], v[202:203]
	v_pk_mul_f32 v[46:47], v[46:47], v[204:205]
	v_cvt_pk_bf16_f32 v40, v72, v40
	v_cvt_pk_bf16_f32 v41, v73, v41
	v_cvt_pk_bf16_f32 v42, v74, v42
	v_cvt_pk_bf16_f32 v43, v75, v43
	v_cvt_pk_bf16_f32 v44, v60, v44
	v_cvt_pk_bf16_f32 v45, v61, v45
	v_cvt_pk_bf16_f32 v46, v62, v46
	v_cvt_pk_bf16_f32 v47, v63, v47
	v_add_u32_e32 v197, 0x120000, v225
	global_store_dwordx4 v197, v[40:43], s[44:45]
	global_store_dwordx4 v197, v[44:47], s[44:45] offset:16
	v_pk_add_f32 v[28:29], v[28:29], v[68:69]
	v_pk_add_f32 v[16:17], v[16:17], v[32:33]
	v_pk_add_f32 v[30:31], v[30:31], v[70:71]
	v_pk_add_f32 v[18:19], v[18:19], v[34:35]
	v_pk_add_f32 v[24:25], v[24:25], v[56:57]
	v_pk_add_f32 v[20:21], v[20:21], v[36:37]
	v_pk_add_f32 v[26:27], v[26:27], v[58:59]
	v_pk_add_f32 v[22:23], v[22:23], v[38:39]
	v_pk_mul_f32 v[28:29], v[28:29], s[68:69]
	v_pk_mul_f32 v[16:17], v[16:17], s[68:69]
	v_pk_mul_f32 v[30:31], v[30:31], s[68:69]
	v_pk_mul_f32 v[18:19], v[18:19], s[68:69]
	v_pk_mul_f32 v[24:25], v[24:25], s[68:69]
	v_pk_mul_f32 v[20:21], v[20:21], s[68:69]
	v_pk_mul_f32 v[26:27], v[26:27], s[68:69]
	v_pk_mul_f32 v[22:23], v[22:23], s[68:69]
	v_exp_f32_e32 v28, v28
	v_exp_f32_e32 v29, v29
	v_exp_f32_e32 v30, v30
	v_exp_f32_e32 v31, v31
	v_exp_f32_e32 v24, v24
	v_exp_f32_e32 v25, v25
	v_exp_f32_e32 v26, v26
	v_exp_f32_e32 v27, v27
	v_exp_f32_e32 v16, v16
	v_exp_f32_e32 v17, v17
	v_exp_f32_e32 v18, v18
	v_exp_f32_e32 v19, v19
	v_exp_f32_e32 v20, v20
	v_exp_f32_e32 v21, v21
	v_exp_f32_e32 v22, v22
	v_exp_f32_e32 v23, v23
	v_pk_add_f32 v[28:29], v[28:29], s[72:73]
	v_pk_add_f32 v[16:17], v[16:17], s[72:73]
	v_pk_add_f32 v[30:31], v[30:31], s[72:73]
	v_pk_add_f32 v[18:19], v[18:19], s[72:73]
	v_pk_add_f32 v[24:25], v[24:25], s[72:73]
	v_pk_add_f32 v[20:21], v[20:21], s[72:73]
	v_pk_add_f32 v[26:27], v[26:27], s[72:73]
	v_pk_add_f32 v[22:23], v[22:23], s[72:73]
	v_rcp_f32_e32 v28, v28
	v_rcp_f32_e32 v29, v29
	v_rcp_f32_e32 v30, v30
	v_rcp_f32_e32 v31, v31
	v_rcp_f32_e32 v24, v24
	v_rcp_f32_e32 v25, v25
	v_rcp_f32_e32 v26, v26
	v_rcp_f32_e32 v27, v27
	v_rcp_f32_e32 v16, v16
	v_rcp_f32_e32 v17, v17
	v_rcp_f32_e32 v18, v18
	v_rcp_f32_e32 v19, v19
	v_rcp_f32_e32 v20, v20
	v_rcp_f32_e32 v21, v21
	v_rcp_f32_e32 v22, v22
	v_rcp_f32_e32 v23, v23
	v_lshlrev_b32_e32 v230, 16, v76
	v_and_b32_e32 v231, 0xffff0000, v76
	v_lshlrev_b32_e32 v234, 16, v77
	v_and_b32_e32 v235, 0xffff0000, v77
	v_lshlrev_b32_e32 v236, 16, v78
	v_and_b32_e32 v237, 0xffff0000, v78
	v_lshlrev_b32_e32 v238, 16, v79
	v_and_b32_e32 v239, 0xffff0000, v79
	v_pk_mul_f32 v[28:29], v[64:65], v[28:29]
	v_pk_mul_f32 v[30:31], v[66:67], v[30:31]
	v_pk_mul_f32 v[24:25], v[52:53], v[24:25]
	v_pk_mul_f32 v[26:27], v[54:55], v[26:27]
	v_pk_mul_f32 v[16:17], v[16:17], v[230:231]
	v_pk_mul_f32 v[18:19], v[18:19], v[234:235]
	v_pk_mul_f32 v[20:21], v[20:21], v[236:237]
	v_pk_mul_f32 v[22:23], v[22:23], v[238:239]
	v_pk_add_f32 v[198:199], v[28:29], v[28:29]
	v_pk_add_f32 v[200:201], v[30:31], v[30:31]
	v_pk_mul_f32 v[206:207], v[198:199], s[70:71]
	v_pk_mul_f32 v[208:209], v[200:201], s[70:71]
	v_pk_fma_f32 v[202:203], v[198:199], s[74:75], v[222:223]
	v_pk_fma_f32 v[204:205], v[200:201], s[74:75], v[222:223]
	v_exp_f32_e32 v206, v206
	v_exp_f32_e32 v207, v207
	v_exp_f32_e32 v208, v208
	v_exp_f32_e32 v209, v209
	v_pk_fma_f32 v[202:203], v[198:199], v[202:203], s[76:77]
	v_pk_fma_f32 v[204:205], v[200:201], v[204:205], s[76:77]
	v_pk_fma_f32 v[202:203], v[198:199], v[202:203], s[72:73]
	v_pk_fma_f32 v[204:205], v[200:201], v[204:205], s[72:73]
	v_pk_mul_f32 v[202:203], v[202:203], v[198:199] neg_lo:[0,1] neg_hi:[0,1]
; __device__ __forceinline__ unsigned pk2(float lo, float hi) { unsigned r; asm("v_cvt_pk_bf16_f32 %0, %1, %2" : "=v"(r) : "v"(lo), "v"(hi)); return r; }
; __device__ __forceinline__ float sigmoidf_(float x) { return __builtin_amdgcn_rcpf(1.0f + __expf(-x)); }
;     __device__ __forceinline__ void operator()(const f32x4 (&acc)[2][2][4][2], const Unit& u, int wr, int wc, int fr, int fq) const {
;     ...
;         for (int ai = 0; ai < 2; ++ai)
; #pragma unroll
;             for (int m = 0; m < 4; ++m) { const size_t off = (size_t)(row0 + ai * HALF + m * 16) * LW + ch0;
;                 float xc[8]; unpack8(xraw[ai][m], xc);
;                 float la[8], uu[8];
; #pragma unroll
;                 for (int n = 0; n < 2; ++n)
; #pragma unroll
;                     for (int j = 0; j < 4; ++j) { const int e = 4 * n + j;
;                         const float r = sigmoidf_(acc[ai][0][m][n][j] + br[e]), ig = sigmoidf_(acc[ai][1][m][n][j] + bi[e]);
;                         const float l = -8.0f * r * sp[e]; la[e] = l;
;                         const float x2 = 2.0f * l;
;                         const float om = x2 > -0.03125f ? -x2 * (1.0f + x2 * (0.5f + x2 * (0.16666667f + x2 * 0.041666668f))) : 1.0f - __expf(x2);
;                         uu[e] = __builtin_amdgcn_sqrtf(om) * (ig * xc[e]); }
;                 u32x4 w0, w1; w0.x = pk2(la[0], uu[0]); w0.y = pk2(la[1], uu[1]); w0.z = pk2(la[2], uu[2]); w0.w = pk2(la[3], uu[3]);
;                 w1.x = pk2(la[4], uu[4]); w1.y = pk2(la[5], uu[5]); w1.z = pk2(la[6], uu[6]); w1.w = pk2(la[7], uu[7]);
;                 *(u32x4*)(LU + off) = w0; *(u32x4*)(LU + off + 4) = w1; }
	v_pk_mul_f32 v[204:205], v[204:205], v[200:201] neg_lo:[0,1] neg_hi:[0,1]
	v_pk_add_f32 v[206:207], s[72:73], v[206:207] neg_lo:[0,1] neg_hi:[0,1]
	v_pk_add_f32 v[208:209], s[72:73], v[208:209] neg_lo:[0,1] neg_hi:[0,1]
	v_cmp_lt_f32_e64 s[78:79], s4, v198
	v_cmp_lt_f32_e64 s[80:81], s4, v199
	v_cmp_lt_f32_e64 s[82:83], s4, v200
	v_cmp_lt_f32_e64 s[24:25], s4, v201
	v_cndmask_b32_e64 v202, v206, v202, s[78:79]
	v_cndmask_b32_e64 v203, v207, v203, s[80:81]
	v_cndmask_b32_e64 v204, v208, v204, s[82:83]
	v_cndmask_b32_e64 v205, v209, v205, s[24:25]
	v_sqrt_f32_e32 v202, v202
	v_sqrt_f32_e32 v203, v203
	v_sqrt_f32_e32 v204, v204
	v_sqrt_f32_e32 v205, v205
	v_pk_mul_f32 v[16:17], v[16:17], v[202:203]
	v_pk_mul_f32 v[18:19], v[18:19], v[204:205]
	v_pk_add_f32 v[198:199], v[24:25], v[24:25]
	v_pk_add_f32 v[200:201], v[26:27], v[26:27]
	v_pk_mul_f32 v[206:207], v[198:199], s[70:71]
	v_pk_mul_f32 v[208:209], v[200:201], s[70:71]
	v_pk_fma_f32 v[202:203], v[198:199], s[74:75], v[222:223]
	v_pk_fma_f32 v[204:205], v[200:201], s[74:75], v[222:223]
	v_exp_f32_e32 v206, v206
	v_exp_f32_e32 v207, v207
	v_exp_f32_e32 v208, v208
	v_exp_f32_e32 v209, v209
	v_pk_fma_f32 v[202:203], v[198:199], v[202:203], s[76:77]
	v_pk_fma_f32 v[204:205], v[200:201], v[204:205], s[76:77]
	v_pk_fma_f32 v[202:203], v[198:199], v[202:203], s[72:73]
	v_pk_fma_f32 v[204:205], v[200:201], v[204:205], s[72:73]
	v_pk_mul_f32 v[202:203], v[202:203], v[198:199] neg_lo:[0,1] neg_hi:[0,1]
	v_pk_mul_f32 v[204:205], v[204:205], v[200:201] neg_lo:[0,1] neg_hi:[0,1]
	v_pk_add_f32 v[206:207], s[72:73], v[206:207] neg_lo:[0,1] neg_hi:[0,1]
	v_pk_add_f32 v[208:209], s[72:73], v[208:209] neg_lo:[0,1] neg_hi:[0,1]
	v_cmp_lt_f32_e64 s[78:79], s4, v198
	v_cmp_lt_f32_e64 s[80:81], s4, v199
	v_cmp_lt_f32_e64 s[82:83], s4, v200
	v_cmp_lt_f32_e64 s[24:25], s4, v201
	v_cndmask_b32_e64 v202, v206, v202, s[78:79]
	v_cndmask_b32_e64 v203, v207, v203, s[80:81]
	v_cndmask_b32_e64 v204, v208, v204, s[82:83]
	v_cndmask_b32_e64 v205, v209, v205, s[24:25]
	v_sqrt_f32_e32 v202, v202
	v_sqrt_f32_e32 v203, v203
	v_sqrt_f32_e32 v204, v204
	v_sqrt_f32_e32 v205, v205
	v_pk_mul_f32 v[20:21], v[20:21], v[202:203]
	v_pk_mul_f32 v[22:23], v[22:23], v[204:205]
	v_cvt_pk_bf16_f32 v16, v28, v16
	v_cvt_pk_bf16_f32 v17, v29, v17
	v_cvt_pk_bf16_f32 v18, v30, v18
	v_cvt_pk_bf16_f32 v19, v31, v19
	v_cvt_pk_bf16_f32 v20, v24, v20
	v_cvt_pk_bf16_f32 v21, v25, v21
	v_cvt_pk_bf16_f32 v22, v26, v22
	v_cvt_pk_bf16_f32 v23, v27, v23
	v_add_u32_e32 v197, 0x140000, v225
	global_store_dwordx4 v197, v[16:19], s[44:45]
	global_store_dwordx4 v197, v[20:23], s[44:45] offset:16
	v_pk_add_f32 v[12:13], v[12:13], v[68:69]
	v_pk_add_f32 v[0:1], v[0:1], v[32:33]
	v_pk_add_f32 v[14:15], v[14:15], v[70:71]
	v_pk_add_f32 v[2:3], v[2:3], v[34:35]
	v_pk_add_f32 v[8:9], v[8:9], v[56:57]
	v_pk_add_f32 v[4:5], v[4:5], v[36:37]
	v_pk_add_f32 v[10:11], v[10:11], v[58:59]
	v_pk_add_f32 v[6:7], v[6:7], v[38:39]
	v_pk_mul_f32 v[12:13], v[12:13], s[68:69]
	v_pk_mul_f32 v[0:1], v[0:1], s[68:69]
	v_pk_mul_f32 v[14:15], v[14:15], s[68:69]
	v_pk_mul_f32 v[2:3], v[2:3], s[68:69]
	v_pk_mul_f32 v[8:9], v[8:9], s[68:69]
	v_pk_mul_f32 v[4:5], v[4:5], s[68:69]
	v_pk_mul_f32 v[10:11], v[10:11], s[68:69]
	v_pk_mul_f32 v[6:7], v[6:7], s[68:69]
	v_exp_f32_e32 v12, v12
	v_exp_f32_e32 v13, v13
	v_exp_f32_e32 v14, v14
	v_exp_f32_e32 v15, v15
	v_exp_f32_e32 v8, v8
	v_exp_f32_e32 v9, v9
	v_exp_f32_e32 v10, v10
	v_exp_f32_e32 v11, v11
	v_exp_f32_e32 v0, v0
	v_exp_f32_e32 v1, v1
	v_exp_f32_e32 v2, v2
	v_exp_f32_e32 v3, v3
	v_exp_f32_e32 v4, v4
	v_exp_f32_e32 v5, v5
	v_exp_f32_e32 v6, v6
	v_exp_f32_e32 v7, v7
	v_pk_add_f32 v[12:13], v[12:13], s[72:73]
	v_pk_add_f32 v[0:1], v[0:1], s[72:73]
	v_pk_add_f32 v[14:15], v[14:15], s[72:73]
	v_pk_add_f32 v[2:3], v[2:3], s[72:73]
	v_pk_add_f32 v[8:9], v[8:9], s[72:73]
	v_pk_add_f32 v[4:5], v[4:5], s[72:73]
	v_pk_add_f32 v[10:11], v[10:11], s[72:73]
	v_pk_add_f32 v[6:7], v[6:7], s[72:73]
	v_rcp_f32_e32 v12, v12
	v_rcp_f32_e32 v13, v13
	v_rcp_f32_e32 v14, v14
	v_rcp_f32_e32 v15, v15
	v_rcp_f32_e32 v8, v8
	v_rcp_f32_e32 v9, v9
	v_rcp_f32_e32 v10, v10
	v_rcp_f32_e32 v11, v11
	v_rcp_f32_e32 v0, v0
	v_rcp_f32_e32 v1, v1
	v_rcp_f32_e32 v2, v2
; __device__ __forceinline__ unsigned pk2(float lo, float hi) { unsigned r; asm("v_cvt_pk_bf16_f32 %0, %1, %2" : "=v"(r) : "v"(lo), "v"(hi)); return r; }
; __device__ __forceinline__ float sigmoidf_(float x) { return __builtin_amdgcn_rcpf(1.0f + __expf(-x)); }
; template <class Epi, class S_t>
; __device__ __forceinline__ void gemm_phase(LAS unsigned char* lds, int lda, int ldb, const S_t& S, const Epi& E) {
;     ...
;         if (!has_next) break;
; #pragma unroll
;         for (int a = 0; a < 2; ++a)
; #pragma unroll
;             for (int b = 0; b < 2; ++b)
; #pragma unroll
;                 for (int m = 0; m < 4; ++m)
; #pragma unroll
;                     for (int n = 0; n < 2; ++n) acc[a][b][m][n] = (f32x4){0.f, 0.f, 0.f, 0.f};
;         cur = nxt; cA = nA; cB = nB; ++ui;
;     __device__ __forceinline__ void operator()(const f32x4 (&acc)[2][2][4][2], const Unit& u, int wr, int wc, int fr, int fq) const {
;     ...
;                     for (int j = 0; j < 4; ++j) { const int e = 4 * n + j;
;                         const float r = sigmoidf_(acc[ai][0][m][n][j] + br[e]), ig = sigmoidf_(acc[ai][1][m][n][j] + bi[e]);
;                         const float l = -8.0f * r * sp[e]; la[e] = l;
;                         const float x2 = 2.0f * l;
;                         const float om = x2 > -0.03125f ? -x2 * (1.0f + x2 * (0.5f + x2 * (0.16666667f + x2 * 0.041666668f))) : 1.0f - __expf(x2);
;                         uu[e] = __builtin_amdgcn_sqrtf(om) * (ig * xc[e]); }
;                 u32x4 w0, w1; w0.x = pk2(la[0], uu[0]); w0.y = pk2(la[1], uu[1]); w0.z = pk2(la[2], uu[2]); w0.w = pk2(la[3], uu[3]);
;                 w1.x = pk2(la[4], uu[4]); w1.y = pk2(la[5], uu[5]); w1.z = pk2(la[6], uu[6]); w1.w = pk2(la[7], uu[7]);
;                 *(u32x4*)(LU + off) = w0; *(u32x4*)(LU + off + 4) = w1; }
	v_rcp_f32_e32 v3, v3
	v_rcp_f32_e32 v4, v4
	v_rcp_f32_e32 v5, v5
	v_rcp_f32_e32 v6, v6
	v_rcp_f32_e32 v7, v7
	v_lshlrev_b32_e32 v230, 16, v48
	v_and_b32_e32 v231, 0xffff0000, v48
	v_lshlrev_b32_e32 v234, 16, v49
	v_and_b32_e32 v235, 0xffff0000, v49
	v_lshlrev_b32_e32 v236, 16, v50
	v_and_b32_e32 v237, 0xffff0000, v50
	v_lshlrev_b32_e32 v238, 16, v51
	v_and_b32_e32 v239, 0xffff0000, v51
	v_pk_mul_f32 v[12:13], v[64:65], v[12:13]
	v_pk_mul_f32 v[14:15], v[66:67], v[14:15]
	v_pk_mul_f32 v[8:9], v[52:53], v[8:9]
	v_pk_mul_f32 v[10:11], v[54:55], v[10:11]
	v_pk_mul_f32 v[0:1], v[0:1], v[230:231]
	v_pk_mul_f32 v[2:3], v[2:3], v[234:235]
	v_pk_mul_f32 v[4:5], v[4:5], v[236:237]
	v_pk_mul_f32 v[6:7], v[6:7], v[238:239]
	v_pk_add_f32 v[198:199], v[12:13], v[12:13]
	v_pk_add_f32 v[200:201], v[14:15], v[14:15]
	v_pk_mul_f32 v[206:207], v[198:199], s[70:71]
	v_pk_mul_f32 v[208:209], v[200:201], s[70:71]
	v_pk_fma_f32 v[202:203], v[198:199], s[74:75], v[222:223]
	v_pk_fma_f32 v[204:205], v[200:201], s[74:75], v[222:223]
	v_exp_f32_e32 v206, v206
	v_exp_f32_e32 v207, v207
	v_exp_f32_e32 v208, v208
	v_exp_f32_e32 v209, v209
	v_pk_fma_f32 v[202:203], v[198:199], v[202:203], s[76:77]
	v_pk_fma_f32 v[204:205], v[200:201], v[204:205], s[76:77]
	v_pk_fma_f32 v[202:203], v[198:199], v[202:203], s[72:73]
	v_pk_fma_f32 v[204:205], v[200:201], v[204:205], s[72:73]
	v_pk_mul_f32 v[202:203], v[202:203], v[198:199] neg_lo:[0,1] neg_hi:[0,1]
	v_pk_mul_f32 v[204:205], v[204:205], v[200:201] neg_lo:[0,1] neg_hi:[0,1]
	v_pk_add_f32 v[206:207], s[72:73], v[206:207] neg_lo:[0,1] neg_hi:[0,1]
	v_pk_add_f32 v[208:209], s[72:73], v[208:209] neg_lo:[0,1] neg_hi:[0,1]
	v_cmp_lt_f32_e64 s[78:79], s4, v198
	v_cmp_lt_f32_e64 s[80:81], s4, v199
	v_cmp_lt_f32_e64 s[82:83], s4, v200
	v_cmp_lt_f32_e64 s[24:25], s4, v201
	v_cndmask_b32_e64 v202, v206, v202, s[78:79]
	v_cndmask_b32_e64 v203, v207, v203, s[80:81]
	v_cndmask_b32_e64 v204, v208, v204, s[82:83]
	v_cndmask_b32_e64 v205, v209, v205, s[24:25]
	v_sqrt_f32_e32 v202, v202
	v_sqrt_f32_e32 v203, v203
	v_sqrt_f32_e32 v204, v204
	v_sqrt_f32_e32 v205, v205
	v_pk_mul_f32 v[0:1], v[0:1], v[202:203]
	v_pk_mul_f32 v[2:3], v[2:3], v[204:205]
	v_pk_add_f32 v[198:199], v[8:9], v[8:9]
	v_pk_add_f32 v[200:201], v[10:11], v[10:11]
	v_pk_mul_f32 v[206:207], v[198:199], s[70:71]
	v_pk_mul_f32 v[208:209], v[200:201], s[70:71]
	v_pk_fma_f32 v[202:203], v[198:199], s[74:75], v[222:223]
	v_pk_fma_f32 v[204:205], v[200:201], s[74:75], v[222:223]
	v_exp_f32_e32 v206, v206
	v_exp_f32_e32 v207, v207
	v_exp_f32_e32 v208, v208
	v_exp_f32_e32 v209, v209
	v_pk_fma_f32 v[202:203], v[198:199], v[202:203], s[76:77]
	v_pk_fma_f32 v[204:205], v[200:201], v[204:205], s[76:77]
	v_pk_fma_f32 v[202:203], v[198:199], v[202:203], s[72:73]
	v_pk_fma_f32 v[204:205], v[200:201], v[204:205], s[72:73]
	v_pk_mul_f32 v[202:203], v[202:203], v[198:199] neg_lo:[0,1] neg_hi:[0,1]
	v_pk_mul_f32 v[204:205], v[204:205], v[200:201] neg_lo:[0,1] neg_hi:[0,1]
	v_pk_add_f32 v[206:207], s[72:73], v[206:207] neg_lo:[0,1] neg_hi:[0,1]
	v_pk_add_f32 v[208:209], s[72:73], v[208:209] neg_lo:[0,1] neg_hi:[0,1]
	v_cmp_lt_f32_e64 s[78:79], s4, v198
	v_cmp_lt_f32_e64 s[80:81], s4, v199
	v_cmp_lt_f32_e64 s[82:83], s4, v200
	v_cmp_lt_f32_e64 s[24:25], s4, v201
	v_cndmask_b32_e64 v202, v206, v202, s[78:79]
	v_cndmask_b32_e64 v203, v207, v203, s[80:81]
	v_cndmask_b32_e64 v204, v208, v204, s[82:83]
	v_cndmask_b32_e64 v205, v209, v205, s[24:25]
	v_sqrt_f32_e32 v202, v202
	v_sqrt_f32_e32 v203, v203
	v_sqrt_f32_e32 v204, v204
	v_sqrt_f32_e32 v205, v205
	v_pk_mul_f32 v[4:5], v[4:5], v[202:203]
	v_pk_mul_f32 v[6:7], v[6:7], v[204:205]
	v_cvt_pk_bf16_f32 v0, v12, v0
	v_cvt_pk_bf16_f32 v1, v13, v1
	v_cvt_pk_bf16_f32 v2, v14, v2
	v_cvt_pk_bf16_f32 v3, v15, v3
	v_cvt_pk_bf16_f32 v4, v8, v4
	v_cvt_pk_bf16_f32 v5, v9, v5
	v_cvt_pk_bf16_f32 v6, v10, v6
	v_cvt_pk_bf16_f32 v7, v11, v7
	s_and_b64 vcc, exec, s[6:7]
	s_mov_b32 s42, s14
	s_mov_b32 s5, s18
	s_mov_b64 s[62:63], s[58:59]
	s_mov_b64 s[60:61], s[56:57]
	v_add_u32_e32 v197, 0x160000, v225
	global_store_dwordx4 v197, v[0:3], s[44:45]
	global_store_dwordx4 v197, v[4:7], s[44:45] offset:16
	s_cbranch_vccnz .LBB0_804
	s_branch .LBB0_544
